# residual/gate epilogues of P2, P7, P8, P10: the single vmcnt(0) after the 16 epilogue loads replaced by counted waits at each tuple's first use; on top of v54
# speedup vs baseline: 1.0119x; 1.0079x over previous
; __device__ __forceinline__ unsigned pk2(float lo, float hi) { f32x2_t v = {lo, hi}; bf16x2_t b = __builtin_convertvector(v, bf16x2_t); return __builtin_bit_cast(unsigned, b); }
; __device__ __forceinline__ float bflo(unsigned w) { return __uint_as_float(w << 16); }
;     __device__ __forceinline__ void operator()(Acc& acc, const Unit& u, int wr, int wc, int fr, int fq) const {
;         const int col0 = u.pn * BM + wc * 32 + 8 * fq;
;         const unsigned xlo = (unsigned)lds_byte(fr, 8 * fq);
;         u32x4 rb[2][4][2];
;         if (RES_BF16) {
; #pragma unroll
;             for (int ai = 0; ai < 2; ++ai)
; #pragma unroll
;                 for (int m = 0; m < 4; ++m)
; #pragma unroll
;                     for (int bj = 0; bj < 2; ++bj) rb[ai][m][bj] = *(const u32x4*)((const char*)XBo + xb_piece(u.pm, u.pn, wr, wc, ai, m, bj) + xlo);
;         }
; #pragma unroll
;         for (int ai = 0; ai < 2; ++ai)
; #pragma unroll
;             for (int m = 0; m < 4; ++m) {
;                 const int row = u.pm * BM + ai * HALF + wr * 64 + m * 16 + fr;
;                 float ss = 0.f;
; #pragma unroll
;                 for (int bj = 0; bj < 2; ++bj) {
;                     const size_t off = (size_t)row * D + col0 + bj * HALF;
;                     f32x4 r0, r1;
;                     if (RES_BF16) { const u32x4 q = rb[ai][m][bj]; r0 = (f32x4){bflo(q.x), bfhi(q.x), bflo(q.y), bfhi(q.y)}; r1 = (f32x4){bflo(q.z), bfhi(q.z), bflo(q.w), bfhi(q.w)}; }
;                     else { r0 = *(const f32x4*)(res_f32 + off); r1 = *(const f32x4*)(res_f32 + off + 4); }
;                     const f32x4 v0 = r0 + acc[ai][bj][m][0] * alpha, v1 = r1 + acc[ai][bj][m][1] * alpha;
;                     u32x4 w; w.x = pk2(v0[0], v0[1]); w.y = pk2(v0[2], v0[3]); w.z = pk2(v1[0], v1[1]); w.w = pk2(v1[2], v1[3]);
;                     *(u32x4*)((char*)XBo + xb_piece(u.pm, u.pn, wr, wc, ai, m, bj) + xlo) = w;
;                     ss += (v0[0] * v0[0] + v0[1] * v0[1]) + (v0[2] * v0[2] + v0[3] * v0[3]) + (v1[0] * v1[0] + v1[1] * v1[1]) + (v1[2] * v1[2] + v1[3] * v1[3]);
;                 }
;                 ss += __shfl_xor(ss, 16); ss += __shfl_xor(ss, 32);
;                 if (ssqp && fq == 0) ssqp[(size_t)row * 16 + u.pn * 4 + wc] = ss;
;                 if (!RES_BF16 && (m & 1)) asm volatile("" ::: "memory");
;             }
.LBB0_543:
	s_lshl_b32 s51, s60, 4
	s_lshl_b32 s50, s26, 2
	s_add_i32 s51, s51, s50
	s_or_b32 s52, s51, s69
	s_ashr_i32 s53, s52, 31
	s_lshl_b64 s[54:55], s[52:53], 15
	v_lshl_add_u64 v[98:99], v[202:203], 0, s[54:55]
	global_load_dwordx4 v[190:193], v[98:99], off
	s_or_b32 s52, s52, 2
	s_ashr_i32 s53, s52, 31
	s_lshl_b64 s[52:53], s[52:53], 15
	v_lshl_add_u64 v[100:101], v[202:203], 0, s[52:53]
	global_load_dwordx4 v[186:189], v[100:101], off
	global_load_dwordx4 v[182:185], v[98:99], off offset:2048
	global_load_dwordx4 v[178:181], v[100:101], off offset:2048
	v_lshl_add_u64 v[98:99], v[204:205], 0, s[54:55]
	global_load_dwordx4 v[174:177], v[98:99], off
	v_lshl_add_u64 v[98:99], v[204:205], 0, s[52:53]
	global_load_dwordx4 v[170:173], v[98:99], off
	v_lshl_add_u64 v[98:99], v[206:207], 0, s[54:55]
	global_load_dwordx4 v[166:169], v[98:99], off
	v_lshl_add_u64 v[98:99], v[206:207], 0, s[52:53]
	global_load_dwordx4 v[154:157], v[98:99], off
	v_lshl_add_u64 v[98:99], v[208:209], 0, s[54:55]
	global_load_dwordx4 v[150:153], v[98:99], off
	v_lshl_add_u64 v[98:99], v[208:209], 0, s[52:53]
	global_load_dwordx4 v[146:149], v[98:99], off
	v_lshl_add_u64 v[98:99], v[210:211], 0, s[54:55]
	global_load_dwordx4 v[142:145], v[98:99], off
	v_lshl_add_u64 v[98:99], v[210:211], 0, s[52:53]
	global_load_dwordx4 v[134:137], v[98:99], off
	v_lshl_add_u64 v[98:99], v[212:213], 0, s[54:55]
	global_load_dwordx4 v[126:129], v[98:99], off
	v_lshl_add_u64 v[98:99], v[212:213], 0, s[52:53]
	global_load_dwordx4 v[122:125], v[98:99], off
	v_lshl_add_u64 v[98:99], v[214:215], 0, s[54:55]
	global_load_dwordx4 v[110:113], v[98:99], off
	v_lshl_add_u64 v[98:99], v[214:215], 0, s[52:53]
	global_load_dwordx4 v[98:101], v[98:99], off
	v_and_b32_e32 v243, 64, v241
	v_xor_b32_e32 v242, 16, v241
	v_add_u32_e32 v243, 64, v243
	v_cmp_lt_i32_e32 vcc, v242, v243
	v_xor_b32_e32 v244, 32, v241
	s_add_u32 s54, s14, s54
	v_cndmask_b32_e32 v242, v241, v242, vcc
	v_cmp_lt_i32_e32 vcc, v244, v243
	s_addc_u32 s55, s15, s55
	s_add_u32 s78, s54, s42
	v_cndmask_b32_e32 v243, v241, v244, vcc
	s_addc_u32 s79, s55, s43
	v_lshlrev_b32_e32 v242, 2, v242
	v_lshlrev_b32_e32 v243, 2, v243
	s_waitcnt vmcnt(15)
	v_lshlrev_b32_e32 v244, 16, v190
	v_and_b32_e32 v245, 0xffff0000, v190
	v_lshlrev_b32_e32 v190, 16, v191
	v_and_b32_e32 v191, 0xffff0000, v191
	v_lshlrev_b32_e32 v246, 16, v192
	v_and_b32_e32 v247, 0xffff0000, v192
	v_lshlrev_b32_e32 v192, 16, v193
	v_and_b32_e32 v193, 0xffff0000, v193
	v_pk_fma_f32 v[164:165], v[164:165], 0.5, v[190:191] op_sel_hi:[1,0,1]
	v_pk_fma_f32 v[190:191], v[162:163], 0.5, v[244:245] op_sel_hi:[1,0,1]
	v_pk_fma_f32 v[192:193], v[160:161], 0.5, v[192:193] op_sel_hi:[1,0,1]
	v_pk_fma_f32 v[244:245], v[158:159], 0.5, v[246:247] op_sel_hi:[1,0,1]
	v_cvt_pk_bf16_f32 v160, v190, v191
	v_cvt_pk_bf16_f32 v161, v164, v165
	v_cvt_pk_bf16_f32 v162, v244, v245
	v_cvt_pk_bf16_f32 v163, v192, v193
	v_lshl_add_u64 v[158:159], s[78:79], 0, v[200:201]
	global_store_dwordx4 v[158:159], v[160:163], off
	s_add_u32 s78, s14, s52
	s_addc_u32 s79, s15, s53
	v_mul_f32_e32 v160, v191, v191
	v_mul_f32_e32 v161, v165, v165
	v_fmac_f32_e32 v160, v190, v190
	v_fmac_f32_e32 v161, v164, v164
	v_add_f32_e32 v160, v160, v161
	v_mul_f32_e32 v161, v245, v245
	v_fmac_f32_e32 v161, v244, v244
	v_add_f32_e32 v160, v161, v160
	v_mul_f32_e32 v161, v193, v193
	v_fmac_f32_e32 v161, v192, v192
	v_add_f32_e32 v190, v161, v160
	s_waitcnt vmcnt(15)
	v_lshlrev_b32_e32 v160, 16, v186
	v_and_b32_e32 v161, 0xffff0000, v186
	v_lshlrev_b32_e32 v162, 16, v187
	v_and_b32_e32 v163, 0xffff0000, v187
	v_lshlrev_b32_e32 v164, 16, v188
	v_and_b32_e32 v165, 0xffff0000, v188
	v_lshlrev_b32_e32 v186, 16, v189
	v_and_b32_e32 v187, 0xffff0000, v189
	s_add_u32 s52, s78, s42
	v_pk_fma_f32 v[162:163], v[140:141], 0.5, v[162:163] op_sel_hi:[1,0,1]
	v_pk_fma_f32 v[160:161], v[138:139], 0.5, v[160:161] op_sel_hi:[1,0,1]
	v_pk_fma_f32 v[132:133], v[132:133], 0.5, v[186:187] op_sel_hi:[1,0,1]
	v_pk_fma_f32 v[164:165], v[130:131], 0.5, v[164:165] op_sel_hi:[1,0,1]
	s_addc_u32 s53, s79, s43
	v_cvt_pk_bf16_f32 v138, v160, v161
	v_cvt_pk_bf16_f32 v139, v162, v163
	v_cvt_pk_bf16_f32 v140, v164, v165
	v_cvt_pk_bf16_f32 v141, v132, v133
	v_lshl_add_u64 v[130:131], s[52:53], 0, v[200:201]
	global_store_dwordx4 v[130:131], v[138:141], off
	v_mul_f32_e32 v133, v133, v133
	v_fmac_f32_e32 v133, v132, v132
	v_mul_f32_e32 v138, v161, v161
	v_mul_f32_e32 v139, v163, v163
	v_fmac_f32_e32 v138, v160, v160
	v_fmac_f32_e32 v139, v162, v162
	v_add_f32_e32 v138, v138, v139
	v_mul_f32_e32 v139, v165, v165
	v_fmac_f32_e32 v139, v164, v164
	v_add_f32_e32 v138, v139, v138
	v_add_f32_e32 v132, v133, v138
	v_add_f32_e32 v132, v190, v132
	ds_bpermute_b32 v133, v242, v132
	s_waitcnt lgkmcnt(0)
	v_add_f32_e32 v132, v132, v133
	ds_bpermute_b32 v133, v243, v132
	s_and_saveexec_b64 s[52:53], s[4:5]
	s_cbranch_execz .LBB0_545
	v_lshl_add_u32 v138, s60, 8, v229
	v_ashrrev_i32_e32 v139, 31, v138
	s_waitcnt lgkmcnt(0)
	v_add_f32_e32 v140, v132, v133
	v_lshlrev_b64 v[132:133], 6, v[138:139]
	s_ashr_i32 s51, s50, 31
	v_lshl_add_u64 v[132:133], s[30:31], 0, v[132:133]
	v_lshl_add_u64 v[132:133], s[50:51], 2, v[132:133]
	s_lshl_b32 s26, s66, 2
	v_lshl_add_u64 v[132:133], v[132:133], 0, s[26:27]
	global_store_dword v[132:133], v140, off
; __device__ __forceinline__ unsigned pk2(float lo, float hi) { f32x2_t v = {lo, hi}; bf16x2_t b = __builtin_convertvector(v, bf16x2_t); return __builtin_bit_cast(unsigned, b); }
; __device__ __forceinline__ float bflo(unsigned w) { return __uint_as_float(w << 16); }
;     __device__ __forceinline__ void operator()(Acc& acc, const Unit& u, int wr, int wc, int fr, int fq) const {
;         const int col0 = u.pn * BM + wc * 32 + 8 * fq;
;         const unsigned xlo = (unsigned)lds_byte(fr, 8 * fq);
;         u32x4 rb[2][4][2];
;         if (RES_BF16) {
; #pragma unroll
;             for (int ai = 0; ai < 2; ++ai)
; #pragma unroll
;                 for (int m = 0; m < 4; ++m)
; #pragma unroll
;                     for (int bj = 0; bj < 2; ++bj) rb[ai][m][bj] = *(const u32x4*)((const char*)XBo + xb_piece(u.pm, u.pn, wr, wc, ai, m, bj) + xlo);
;         }
; #pragma unroll
;         for (int ai = 0; ai < 2; ++ai)
; #pragma unroll
;             for (int m = 0; m < 4; ++m) {
;                 const int row = u.pm * BM + ai * HALF + wr * 64 + m * 16 + fr;
;                 float ss = 0.f;
; #pragma unroll
;                 for (int bj = 0; bj < 2; ++bj) {
;                     const size_t off = (size_t)row * D + col0 + bj * HALF;
;                     f32x4 r0, r1;
;                     if (RES_BF16) { const u32x4 q = rb[ai][m][bj]; r0 = (f32x4){bflo(q.x), bfhi(q.x), bflo(q.y), bfhi(q.y)}; r1 = (f32x4){bflo(q.z), bfhi(q.z), bflo(q.w), bfhi(q.w)}; }
;                     else { r0 = *(const f32x4*)(res_f32 + off); r1 = *(const f32x4*)(res_f32 + off + 4); }
;                     const f32x4 v0 = r0 + acc[ai][bj][m][0] * alpha, v1 = r1 + acc[ai][bj][m][1] * alpha;
;                     u32x4 w; w.x = pk2(v0[0], v0[1]); w.y = pk2(v0[2], v0[3]); w.z = pk2(v1[0], v1[1]); w.w = pk2(v1[2], v1[3]);
;                     *(u32x4*)((char*)XBo + xb_piece(u.pm, u.pn, wr, wc, ai, m, bj) + xlo) = w;
;                     ss += (v0[0] * v0[0] + v0[1] * v0[1]) + (v0[2] * v0[2] + v0[3] * v0[3]) + (v1[0] * v1[0] + v1[1] * v1[1]) + (v1[2] * v1[2] + v1[3] * v1[3]);
;                 }
;                 ss += __shfl_xor(ss, 16); ss += __shfl_xor(ss, 32);
;                 if (ssqp && fq == 0) ssqp[(size_t)row * 16 + u.pn * 4 + wc] = ss;
;                 if (!RES_BF16 && (m & 1)) asm volatile("" ::: "memory");
;             }
.LBB0_545:
	s_or_b64 exec, exec, s[52:53]
	s_waitcnt vmcnt(15)
	v_lshlrev_b32_e32 v132, 16, v182
	s_waitcnt lgkmcnt(0)
	v_and_b32_e32 v133, 0xffff0000, v182
	v_lshlrev_b32_e32 v138, 16, v183
	v_and_b32_e32 v139, 0xffff0000, v183
	v_lshlrev_b32_e32 v140, 16, v184
	v_and_b32_e32 v141, 0xffff0000, v184
	v_lshlrev_b32_e32 v160, 16, v185
	v_and_b32_e32 v161, 0xffff0000, v185
	v_pk_fma_f32 v[118:119], v[118:119], 0.5, v[132:133] op_sel_hi:[1,0,1]
	v_pk_fma_f32 v[120:121], v[120:121], 0.5, v[138:139] op_sel_hi:[1,0,1]
	v_pk_fma_f32 v[132:133], v[116:117], 0.5, v[160:161] op_sel_hi:[1,0,1]
	v_pk_fma_f32 v[116:117], v[114:115], 0.5, v[140:141] op_sel_hi:[1,0,1]
	v_cvt_pk_bf16_f32 v114, v118, v119
	v_mul_f32_e32 v119, v119, v119
	v_fmac_f32_e32 v119, v118, v118
	v_mul_f32_e32 v118, v121, v121
	v_fmac_f32_e32 v118, v120, v120
	v_add_f32_e32 v118, v119, v118
	v_mul_f32_e32 v119, v117, v117
	v_fmac_f32_e32 v119, v116, v116
	v_add_f32_e32 v118, v119, v118
	v_mul_f32_e32 v119, v133, v133
	v_fmac_f32_e32 v119, v132, v132
	v_cvt_pk_bf16_f32 v115, v120, v121
	v_add_f32_e32 v160, v119, v118
	s_waitcnt vmcnt(14)
	v_lshlrev_b32_e32 v118, 16, v178
	v_and_b32_e32 v119, 0xffff0000, v178
	v_lshlrev_b32_e32 v120, 16, v179
	v_and_b32_e32 v121, 0xffff0000, v179
	v_lshlrev_b32_e32 v138, 16, v180
	v_and_b32_e32 v139, 0xffff0000, v180
	v_pk_fma_f32 v[108:109], v[108:109], 0.5, v[120:121] op_sel_hi:[1,0,1]
	v_pk_fma_f32 v[106:107], v[106:107], 0.5, v[118:119] op_sel_hi:[1,0,1]
	v_pk_fma_f32 v[120:121], v[102:103], 0.5, v[138:139] op_sel_hi:[1,0,1]
	v_mul_f32_e32 v102, v107, v107
	v_mul_f32_e32 v103, v109, v109
	v_fmac_f32_e32 v102, v106, v106
	v_fmac_f32_e32 v103, v108, v108
	v_lshlrev_b32_e32 v140, 16, v181
	v_and_b32_e32 v141, 0xffff0000, v181
	v_add_f32_e32 v102, v102, v103
	v_mul_f32_e32 v103, v121, v121
	v_pk_fma_f32 v[118:119], v[104:105], 0.5, v[140:141] op_sel_hi:[1,0,1]
	v_fmac_f32_e32 v103, v120, v120
	v_add_f32_e32 v102, v103, v102
	v_mul_f32_e32 v103, v119, v119
	v_fmac_f32_e32 v103, v118, v118
	v_add_f32_e32 v102, v103, v102
	v_add_f32_e32 v102, v160, v102
	ds_bpermute_b32 v103, v242, v102
	v_cvt_pk_bf16_f32 v116, v116, v117
	v_cvt_pk_bf16_f32 v117, v132, v133
	v_cvt_pk_bf16_f32 v104, v106, v107
	v_cvt_pk_bf16_f32 v105, v108, v109
	s_waitcnt lgkmcnt(0)
	v_add_f32_e32 v102, v102, v103
	ds_bpermute_b32 v103, v243, v102
	v_cvt_pk_bf16_f32 v106, v120, v121
	v_cvt_pk_bf16_f32 v107, v118, v119
	global_store_dwordx4 v[158:159], v[114:117], off offset:2048
	global_store_dwordx4 v[130:131], v[104:107], off offset:2048
	s_and_saveexec_b64 s[52:53], s[4:5]
	s_cbranch_execz .LBB0_547
	v_lshl_add_u32 v104, s60, 8, v231
	v_ashrrev_i32_e32 v105, 31, v104
	s_waitcnt lgkmcnt(0)
	v_add_f32_e32 v106, v102, v103
	v_lshlrev_b64 v[102:103], 6, v[104:105]
	s_ashr_i32 s51, s50, 31
	v_lshl_add_u64 v[102:103], s[30:31], 0, v[102:103]
	v_lshl_add_u64 v[102:103], s[50:51], 2, v[102:103]
	s_lshl_b32 s26, s66, 2
	v_lshl_add_u64 v[102:103], v[102:103], 0, s[26:27]
	global_store_dword v[102:103], v106, off
.LBB0_547:
	s_or_b64 exec, exec, s[52:53]
	s_waitcnt vmcnt(15)
	v_lshlrev_b32_e32 v102, 16, v174
	s_waitcnt lgkmcnt(0)
	v_and_b32_e32 v103, 0xffff0000, v174
	v_lshlrev_b32_e32 v104, 16, v175
	v_and_b32_e32 v105, 0xffff0000, v175
	v_lshlrev_b32_e32 v106, 16, v176
	v_and_b32_e32 v107, 0xffff0000, v176
	v_lshlrev_b32_e32 v108, 16, v177
	v_and_b32_e32 v109, 0xffff0000, v177
	s_add_u32 s52, s54, s46
	v_pk_fma_f32 v[96:97], v[96:97], 0.5, v[104:105] op_sel_hi:[1,0,1]
	v_pk_fma_f32 v[94:95], v[94:95], 0.5, v[102:103] op_sel_hi:[1,0,1]
	v_pk_fma_f32 v[102:103], v[92:93], 0.5, v[108:109] op_sel_hi:[1,0,1]
	v_pk_fma_f32 v[104:105], v[90:91], 0.5, v[106:107] op_sel_hi:[1,0,1]
	s_addc_u32 s53, s55, s47
	v_cvt_pk_bf16_f32 v90, v94, v95
	v_cvt_pk_bf16_f32 v91, v96, v97
	v_cvt_pk_bf16_f32 v92, v104, v105
	v_cvt_pk_bf16_f32 v93, v102, v103
	v_lshl_add_u64 v[106:107], s[52:53], 0, v[200:201]
	global_store_dwordx4 v[106:107], v[90:93], off
	s_add_u32 s52, s78, s46
	s_addc_u32 s53, s79, s47
	v_mul_f32_e32 v90, v95, v95
	v_mul_f32_e32 v91, v97, v97
	v_fmac_f32_e32 v90, v94, v94
	v_fmac_f32_e32 v91, v96, v96
	v_add_f32_e32 v90, v90, v91
	v_mul_f32_e32 v91, v105, v105
	v_fmac_f32_e32 v91, v104, v104
	v_add_f32_e32 v90, v91, v90
	v_mul_f32_e32 v91, v103, v103
	v_fmac_f32_e32 v91, v102, v102
	v_add_f32_e32 v102, v91, v90
	s_waitcnt vmcnt(15)
	v_lshlrev_b32_e32 v90, 16, v170
	v_and_b32_e32 v91, 0xffff0000, v170
	v_lshlrev_b32_e32 v92, 16, v171
	v_and_b32_e32 v93, 0xffff0000, v171
	v_lshlrev_b32_e32 v96, 16, v173
	v_and_b32_e32 v97, 0xffff0000, v173
	v_pk_fma_f32 v[88:89], v[88:89], 0.5, v[92:93] op_sel_hi:[1,0,1]
	v_pk_fma_f32 v[86:87], v[86:87], 0.5, v[90:91] op_sel_hi:[1,0,1]
	v_lshlrev_b32_e32 v94, 16, v172
	v_and_b32_e32 v95, 0xffff0000, v172
	v_pk_fma_f32 v[90:91], v[84:85], 0.5, v[96:97] op_sel_hi:[1,0,1]
	v_mul_f32_e32 v84, v87, v87
	v_mul_f32_e32 v85, v89, v89
	v_pk_fma_f32 v[82:83], v[82:83], 0.5, v[94:95] op_sel_hi:[1,0,1]
	v_fmac_f32_e32 v84, v86, v86
	v_fmac_f32_e32 v85, v88, v88
	v_add_f32_e32 v84, v84, v85
	v_mul_f32_e32 v85, v83, v83
	v_fmac_f32_e32 v85, v82, v82
	v_add_f32_e32 v84, v85, v84
	v_mul_f32_e32 v85, v91, v91
	v_fmac_f32_e32 v85, v90, v90
	v_add_f32_e32 v84, v85, v84
	v_add_f32_e32 v92, v102, v84
	ds_bpermute_b32 v93, v242, v92
	v_cvt_pk_bf16_f32 v84, v86, v87
	v_cvt_pk_bf16_f32 v86, v82, v83
	v_cvt_pk_bf16_f32 v85, v88, v89
	v_cvt_pk_bf16_f32 v87, v90, v91
	s_waitcnt lgkmcnt(0)
	v_add_f32_e32 v82, v92, v93
	ds_bpermute_b32 v83, v243, v82
	v_lshl_add_u64 v[88:89], s[52:53], 0, v[200:201]
	global_store_dwordx4 v[88:89], v[84:87], off
	s_and_saveexec_b64 s[52:53], s[4:5]
	s_cbranch_execz .LBB0_549
	v_lshl_add_u32 v84, s60, 8, v232
	v_ashrrev_i32_e32 v85, 31, v84
	s_waitcnt lgkmcnt(0)
	v_add_f32_e32 v86, v82, v83
	v_lshlrev_b64 v[82:83], 6, v[84:85]
	s_ashr_i32 s51, s50, 31
	v_lshl_add_u64 v[82:83], s[30:31], 0, v[82:83]
	v_lshl_add_u64 v[82:83], s[50:51], 2, v[82:83]
	s_lshl_b32 s26, s66, 2
	v_lshl_add_u64 v[82:83], v[82:83], 0, s[26:27]
	global_store_dword v[82:83], v86, off
; __device__ __forceinline__ unsigned pk2(float lo, float hi) { f32x2_t v = {lo, hi}; bf16x2_t b = __builtin_convertvector(v, bf16x2_t); return __builtin_bit_cast(unsigned, b); }
; __device__ __forceinline__ float bflo(unsigned w) { return __uint_as_float(w << 16); }
;     __device__ __forceinline__ void operator()(Acc& acc, const Unit& u, int wr, int wc, int fr, int fq) const {
;         const int col0 = u.pn * BM + wc * 32 + 8 * fq;
;         const unsigned xlo = (unsigned)lds_byte(fr, 8 * fq);
;         u32x4 rb[2][4][2];
;         if (RES_BF16) {
; #pragma unroll
;             for (int ai = 0; ai < 2; ++ai)
; #pragma unroll
;                 for (int m = 0; m < 4; ++m)
; #pragma unroll
;                     for (int bj = 0; bj < 2; ++bj) rb[ai][m][bj] = *(const u32x4*)((const char*)XBo + xb_piece(u.pm, u.pn, wr, wc, ai, m, bj) + xlo);
;         }
; #pragma unroll
;         for (int ai = 0; ai < 2; ++ai)
; #pragma unroll
;             for (int m = 0; m < 4; ++m) {
;                 const int row = u.pm * BM + ai * HALF + wr * 64 + m * 16 + fr;
;                 float ss = 0.f;
; #pragma unroll
;                 for (int bj = 0; bj < 2; ++bj) {
;                     const size_t off = (size_t)row * D + col0 + bj * HALF;
;                     f32x4 r0, r1;
;                     if (RES_BF16) { const u32x4 q = rb[ai][m][bj]; r0 = (f32x4){bflo(q.x), bfhi(q.x), bflo(q.y), bfhi(q.y)}; r1 = (f32x4){bflo(q.z), bfhi(q.z), bflo(q.w), bfhi(q.w)}; }
;                     else { r0 = *(const f32x4*)(res_f32 + off); r1 = *(const f32x4*)(res_f32 + off + 4); }
;                     const f32x4 v0 = r0 + acc[ai][bj][m][0] * alpha, v1 = r1 + acc[ai][bj][m][1] * alpha;
;                     u32x4 w; w.x = pk2(v0[0], v0[1]); w.y = pk2(v0[2], v0[3]); w.z = pk2(v1[0], v1[1]); w.w = pk2(v1[2], v1[3]);
;                     *(u32x4*)((char*)XBo + xb_piece(u.pm, u.pn, wr, wc, ai, m, bj) + xlo) = w;
;                     ss += (v0[0] * v0[0] + v0[1] * v0[1]) + (v0[2] * v0[2] + v0[3] * v0[3]) + (v1[0] * v1[0] + v1[1] * v1[1]) + (v1[2] * v1[2] + v1[3] * v1[3]);
;                 }
;                 ss += __shfl_xor(ss, 16); ss += __shfl_xor(ss, 32);
;                 if (ssqp && fq == 0) ssqp[(size_t)row * 16 + u.pn * 4 + wc] = ss;
;                 if (!RES_BF16 && (m & 1)) asm volatile("" ::: "memory");
;             }
.LBB0_549:
	s_or_b64 exec, exec, s[52:53]
	s_waitcnt vmcnt(15)
	v_lshlrev_b32_e32 v82, 16, v166
	s_waitcnt lgkmcnt(0)
	v_and_b32_e32 v83, 0xffff0000, v166
	v_lshlrev_b32_e32 v84, 16, v167
	v_and_b32_e32 v85, 0xffff0000, v167
	v_lshlrev_b32_e32 v86, 16, v168
	v_and_b32_e32 v87, 0xffff0000, v168
	v_lshlrev_b32_e32 v88, 16, v169
	v_and_b32_e32 v89, 0xffff0000, v169
	s_add_u32 s52, s54, s44
	v_pk_fma_f32 v[80:81], v[80:81], 0.5, v[84:85] op_sel_hi:[1,0,1]
	v_pk_fma_f32 v[78:79], v[78:79], 0.5, v[82:83] op_sel_hi:[1,0,1]
	v_pk_fma_f32 v[82:83], v[76:77], 0.5, v[88:89] op_sel_hi:[1,0,1]
	v_pk_fma_f32 v[84:85], v[74:75], 0.5, v[86:87] op_sel_hi:[1,0,1]
	s_addc_u32 s53, s55, s45
	v_cvt_pk_bf16_f32 v74, v78, v79
	v_cvt_pk_bf16_f32 v75, v80, v81
	v_cvt_pk_bf16_f32 v76, v84, v85
	v_cvt_pk_bf16_f32 v77, v82, v83
	v_lshl_add_u64 v[86:87], s[52:53], 0, v[200:201]
	global_store_dwordx4 v[86:87], v[74:77], off
	s_add_u32 s52, s78, s44
	s_addc_u32 s53, s79, s45
	v_mul_f32_e32 v74, v79, v79
	v_mul_f32_e32 v75, v81, v81
	v_fmac_f32_e32 v74, v78, v78
	v_fmac_f32_e32 v75, v80, v80
	v_add_f32_e32 v74, v74, v75
	v_mul_f32_e32 v75, v85, v85
	v_fmac_f32_e32 v75, v84, v84
	v_add_f32_e32 v74, v75, v74
	v_mul_f32_e32 v75, v83, v83
	v_fmac_f32_e32 v75, v82, v82
	v_add_f32_e32 v82, v75, v74
	s_waitcnt vmcnt(15)
	v_lshlrev_b32_e32 v74, 16, v154
	v_and_b32_e32 v75, 0xffff0000, v154
	v_lshlrev_b32_e32 v76, 16, v155
	v_and_b32_e32 v77, 0xffff0000, v155
	v_lshlrev_b32_e32 v80, 16, v157
	v_and_b32_e32 v81, 0xffff0000, v157
	v_pk_fma_f32 v[72:73], v[72:73], 0.5, v[76:77] op_sel_hi:[1,0,1]
	v_pk_fma_f32 v[70:71], v[70:71], 0.5, v[74:75] op_sel_hi:[1,0,1]
	v_lshlrev_b32_e32 v78, 16, v156
	v_and_b32_e32 v79, 0xffff0000, v156
	v_pk_fma_f32 v[74:75], v[68:69], 0.5, v[80:81] op_sel_hi:[1,0,1]
	v_mul_f32_e32 v68, v71, v71
	v_mul_f32_e32 v69, v73, v73
	v_pk_fma_f32 v[66:67], v[66:67], 0.5, v[78:79] op_sel_hi:[1,0,1]
	v_fmac_f32_e32 v68, v70, v70
	v_fmac_f32_e32 v69, v72, v72
	v_add_f32_e32 v68, v68, v69
	v_mul_f32_e32 v69, v67, v67
	v_fmac_f32_e32 v69, v66, v66
	v_add_f32_e32 v68, v69, v68
	v_mul_f32_e32 v69, v75, v75
	v_fmac_f32_e32 v69, v74, v74
	v_add_f32_e32 v68, v69, v68
	v_add_f32_e32 v76, v82, v68
	ds_bpermute_b32 v77, v242, v76
	v_cvt_pk_bf16_f32 v68, v70, v71
	v_cvt_pk_bf16_f32 v70, v66, v67
	v_cvt_pk_bf16_f32 v69, v72, v73
	v_cvt_pk_bf16_f32 v71, v74, v75
	s_waitcnt lgkmcnt(0)
	v_add_f32_e32 v66, v76, v77
	ds_bpermute_b32 v67, v243, v66
	v_lshl_add_u64 v[72:73], s[52:53], 0, v[200:201]
	global_store_dwordx4 v[72:73], v[68:71], off
	s_and_saveexec_b64 s[52:53], s[4:5]
	s_cbranch_execz .LBB0_551
	v_lshl_add_u32 v68, s60, 8, v233
	v_ashrrev_i32_e32 v69, 31, v68
	s_waitcnt lgkmcnt(0)
	v_add_f32_e32 v70, v66, v67
	v_lshlrev_b64 v[66:67], 6, v[68:69]
	s_ashr_i32 s51, s50, 31
	v_lshl_add_u64 v[66:67], s[30:31], 0, v[66:67]
	v_lshl_add_u64 v[66:67], s[50:51], 2, v[66:67]
	s_lshl_b32 s26, s66, 2
	v_lshl_add_u64 v[66:67], v[66:67], 0, s[26:27]
	global_store_dword v[66:67], v70, off
.LBB0_551:
	s_or_b64 exec, exec, s[52:53]
	s_waitcnt vmcnt(15)
	v_lshlrev_b32_e32 v66, 16, v150
	s_waitcnt lgkmcnt(0)
	v_and_b32_e32 v67, 0xffff0000, v150
	v_lshlrev_b32_e32 v68, 16, v151
	v_and_b32_e32 v69, 0xffff0000, v151
	v_lshlrev_b32_e32 v70, 16, v152
	v_and_b32_e32 v71, 0xffff0000, v152
	v_lshlrev_b32_e32 v72, 16, v153
	v_and_b32_e32 v73, 0xffff0000, v153
	v_pk_fma_f32 v[64:65], v[64:65], 0.5, v[68:69] op_sel_hi:[1,0,1]
	v_pk_fma_f32 v[66:67], v[62:63], 0.5, v[66:67] op_sel_hi:[1,0,1]
	v_pk_fma_f32 v[68:69], v[60:61], 0.5, v[72:73] op_sel_hi:[1,0,1]
	v_pk_fma_f32 v[70:71], v[58:59], 0.5, v[70:71] op_sel_hi:[1,0,1]
	v_add_co_u32_e32 v58, vcc, s65, v158
	v_cvt_pk_bf16_f32 v60, v66, v67
	v_cvt_pk_bf16_f32 v61, v64, v65
	v_cvt_pk_bf16_f32 v62, v70, v71
	v_cvt_pk_bf16_f32 v63, v68, v69
	v_addc_co_u32_e32 v59, vcc, 0, v159, vcc
	global_store_dwordx4 v[58:59], v[60:63], off
	s_nop 1
	v_mul_f32_e32 v60, v67, v67
	v_mul_f32_e32 v61, v65, v65
	v_fmac_f32_e32 v60, v66, v66
	v_fmac_f32_e32 v61, v64, v64
	v_add_f32_e32 v60, v60, v61
	v_mul_f32_e32 v61, v71, v71
	v_fmac_f32_e32 v61, v70, v70
	v_add_f32_e32 v60, v61, v60
	v_mul_f32_e32 v61, v69, v69
	v_fmac_f32_e32 v61, v68, v68
	v_add_f32_e32 v68, v61, v60
	s_waitcnt vmcnt(15)
	v_lshlrev_b32_e32 v60, 16, v146
	v_and_b32_e32 v61, 0xffff0000, v146
	v_lshlrev_b32_e32 v62, 16, v147
	v_and_b32_e32 v63, 0xffff0000, v147
	v_pk_fma_f32 v[56:57], v[56:57], 0.5, v[62:63] op_sel_hi:[1,0,1]
	v_pk_fma_f32 v[54:55], v[54:55], 0.5, v[60:61] op_sel_hi:[1,0,1]
	v_lshlrev_b32_e32 v64, 16, v148
	v_and_b32_e32 v65, 0xffff0000, v148
	v_mul_f32_e32 v60, v55, v55
	v_mul_f32_e32 v61, v57, v57
	v_pk_fma_f32 v[50:51], v[50:51], 0.5, v[64:65] op_sel_hi:[1,0,1]
	v_fmac_f32_e32 v60, v54, v54
	v_fmac_f32_e32 v61, v56, v56
	v_lshlrev_b32_e32 v66, 16, v149
	v_and_b32_e32 v67, 0xffff0000, v149
	v_add_f32_e32 v60, v60, v61
	v_mul_f32_e32 v61, v51, v51
	v_pk_fma_f32 v[52:53], v[52:53], 0.5, v[66:67] op_sel_hi:[1,0,1]
	v_fmac_f32_e32 v61, v50, v50
	v_add_f32_e32 v60, v61, v60
	v_mul_f32_e32 v61, v53, v53
	v_fmac_f32_e32 v61, v52, v52
	v_add_f32_e32 v60, v61, v60
	v_add_f32_e32 v60, v68, v60
	ds_bpermute_b32 v61, v242, v60
	v_cvt_pk_bf16_f32 v54, v54, v55
	v_cvt_pk_bf16_f32 v55, v56, v57
	v_cvt_pk_bf16_f32 v57, v52, v53
	v_cvt_pk_bf16_f32 v56, v50, v51
	s_waitcnt lgkmcnt(0)
	v_add_f32_e32 v52, v60, v61
	ds_bpermute_b32 v53, v243, v52
	v_add_co_u32_e32 v50, vcc, s65, v130
	s_nop 1
	v_addc_co_u32_e32 v51, vcc, 0, v131, vcc
	global_store_dwordx4 v[50:51], v[54:57], off
	s_and_saveexec_b64 s[52:53], s[4:5]
	s_cbranch_execz .LBB0_553
	v_lshl_add_u32 v54, s60, 8, v234
	v_ashrrev_i32_e32 v55, 31, v54
	s_waitcnt lgkmcnt(0)
	v_add_f32_e32 v56, v52, v53
	v_lshlrev_b64 v[52:53], 6, v[54:55]
	s_ashr_i32 s51, s50, 31
	v_lshl_add_u64 v[52:53], s[30:31], 0, v[52:53]
	v_lshl_add_u64 v[52:53], s[50:51], 2, v[52:53]
	s_lshl_b32 s26, s66, 2
	v_lshl_add_u64 v[52:53], v[52:53], 0, s[26:27]
	global_store_dword v[52:53], v56, off
; __device__ __forceinline__ unsigned pk2(float lo, float hi) { f32x2_t v = {lo, hi}; bf16x2_t b = __builtin_convertvector(v, bf16x2_t); return __builtin_bit_cast(unsigned, b); }
; __device__ __forceinline__ float bflo(unsigned w) { return __uint_as_float(w << 16); }
;     __device__ __forceinline__ void operator()(Acc& acc, const Unit& u, int wr, int wc, int fr, int fq) const {
;         const int col0 = u.pn * BM + wc * 32 + 8 * fq;
;         const unsigned xlo = (unsigned)lds_byte(fr, 8 * fq);
;         u32x4 rb[2][4][2];
;         if (RES_BF16) {
; #pragma unroll
;             for (int ai = 0; ai < 2; ++ai)
; #pragma unroll
;                 for (int m = 0; m < 4; ++m)
; #pragma unroll
;                     for (int bj = 0; bj < 2; ++bj) rb[ai][m][bj] = *(const u32x4*)((const char*)XBo + xb_piece(u.pm, u.pn, wr, wc, ai, m, bj) + xlo);
;         }
; #pragma unroll
;         for (int ai = 0; ai < 2; ++ai)
; #pragma unroll
;             for (int m = 0; m < 4; ++m) {
;                 const int row = u.pm * BM + ai * HALF + wr * 64 + m * 16 + fr;
;                 float ss = 0.f;
; #pragma unroll
;                 for (int bj = 0; bj < 2; ++bj) {
;                     const size_t off = (size_t)row * D + col0 + bj * HALF;
;                     f32x4 r0, r1;
;                     if (RES_BF16) { const u32x4 q = rb[ai][m][bj]; r0 = (f32x4){bflo(q.x), bfhi(q.x), bflo(q.y), bfhi(q.y)}; r1 = (f32x4){bflo(q.z), bfhi(q.z), bflo(q.w), bfhi(q.w)}; }
;                     else { r0 = *(const f32x4*)(res_f32 + off); r1 = *(const f32x4*)(res_f32 + off + 4); }
;                     const f32x4 v0 = r0 + acc[ai][bj][m][0] * alpha, v1 = r1 + acc[ai][bj][m][1] * alpha;
;                     u32x4 w; w.x = pk2(v0[0], v0[1]); w.y = pk2(v0[2], v0[3]); w.z = pk2(v1[0], v1[1]); w.w = pk2(v1[2], v1[3]);
;                     *(u32x4*)((char*)XBo + xb_piece(u.pm, u.pn, wr, wc, ai, m, bj) + xlo) = w;
;                     ss += (v0[0] * v0[0] + v0[1] * v0[1]) + (v0[2] * v0[2] + v0[3] * v0[3]) + (v1[0] * v1[0] + v1[1] * v1[1]) + (v1[2] * v1[2] + v1[3] * v1[3]);
;                 }
;                 ss += __shfl_xor(ss, 16); ss += __shfl_xor(ss, 32);
;                 if (ssqp && fq == 0) ssqp[(size_t)row * 16 + u.pn * 4 + wc] = ss;
;                 if (!RES_BF16 && (m & 1)) asm volatile("" ::: "memory");
;             }
.LBB0_553:
	s_or_b64 exec, exec, s[52:53]
	s_waitcnt vmcnt(15)
	v_lshlrev_b32_e32 v52, 16, v142
	s_waitcnt lgkmcnt(0)
	v_and_b32_e32 v53, 0xffff0000, v142
	v_lshlrev_b32_e32 v54, 16, v143
	v_and_b32_e32 v55, 0xffff0000, v143
	v_lshlrev_b32_e32 v56, 16, v144
	v_and_b32_e32 v57, 0xffff0000, v144
	v_lshlrev_b32_e32 v60, 16, v145
	v_and_b32_e32 v61, 0xffff0000, v145
	v_pk_fma_f32 v[46:47], v[46:47], 0.5, v[52:53] op_sel_hi:[1,0,1]
	v_pk_fma_f32 v[48:49], v[48:49], 0.5, v[54:55] op_sel_hi:[1,0,1]
	v_pk_fma_f32 v[52:53], v[44:45], 0.5, v[60:61] op_sel_hi:[1,0,1]
	v_pk_fma_f32 v[44:45], v[42:43], 0.5, v[56:57] op_sel_hi:[1,0,1]
	v_cvt_pk_bf16_f32 v42, v46, v47
	v_mul_f32_e32 v47, v47, v47
	v_fmac_f32_e32 v47, v46, v46
	v_mul_f32_e32 v46, v49, v49
	v_fmac_f32_e32 v46, v48, v48
	v_add_f32_e32 v46, v47, v46
	v_mul_f32_e32 v47, v45, v45
	v_fmac_f32_e32 v47, v44, v44
	v_add_f32_e32 v46, v47, v46
	v_mul_f32_e32 v47, v53, v53
	v_fmac_f32_e32 v47, v52, v52
	v_cvt_pk_bf16_f32 v43, v48, v49
	v_add_f32_e32 v60, v47, v46
	s_waitcnt vmcnt(14)
	v_lshlrev_b32_e32 v46, 16, v134
	v_and_b32_e32 v47, 0xffff0000, v134
	v_lshlrev_b32_e32 v48, 16, v135
	v_and_b32_e32 v49, 0xffff0000, v135
	v_lshlrev_b32_e32 v54, 16, v136
	v_and_b32_e32 v55, 0xffff0000, v136
	v_pk_fma_f32 v[40:41], v[40:41], 0.5, v[48:49] op_sel_hi:[1,0,1]
	v_pk_fma_f32 v[38:39], v[38:39], 0.5, v[46:47] op_sel_hi:[1,0,1]
	v_pk_fma_f32 v[48:49], v[34:35], 0.5, v[54:55] op_sel_hi:[1,0,1]
	v_mul_f32_e32 v34, v39, v39
	v_mul_f32_e32 v35, v41, v41
	v_fmac_f32_e32 v34, v38, v38
	v_fmac_f32_e32 v35, v40, v40
	v_lshlrev_b32_e32 v56, 16, v137
	v_and_b32_e32 v57, 0xffff0000, v137
	v_add_f32_e32 v34, v34, v35
	v_mul_f32_e32 v35, v49, v49
	v_pk_fma_f32 v[46:47], v[36:37], 0.5, v[56:57] op_sel_hi:[1,0,1]
	v_fmac_f32_e32 v35, v48, v48
	v_add_f32_e32 v34, v35, v34
	v_mul_f32_e32 v35, v47, v47
	v_fmac_f32_e32 v35, v46, v46
	v_add_f32_e32 v34, v35, v34
	v_add_f32_e32 v34, v60, v34
	ds_bpermute_b32 v35, v242, v34
	v_cvt_pk_bf16_f32 v44, v44, v45
	v_cvt_pk_bf16_f32 v45, v52, v53
	v_cvt_pk_bf16_f32 v36, v38, v39
	v_cvt_pk_bf16_f32 v37, v40, v41
	s_waitcnt lgkmcnt(0)
	v_add_f32_e32 v34, v34, v35
	ds_bpermute_b32 v35, v243, v34
	v_cvt_pk_bf16_f32 v38, v48, v49
	v_cvt_pk_bf16_f32 v39, v46, v47
	global_store_dwordx4 v[58:59], v[42:45], off offset:2048
	global_store_dwordx4 v[50:51], v[36:39], off offset:2048
	s_and_saveexec_b64 s[52:53], s[4:5]
	s_cbranch_execz .LBB0_555
	v_lshl_add_u32 v36, s60, 8, v235
	v_ashrrev_i32_e32 v37, 31, v36
	s_waitcnt lgkmcnt(0)
	v_add_f32_e32 v38, v34, v35
	v_lshlrev_b64 v[34:35], 6, v[36:37]
	s_ashr_i32 s51, s50, 31
	v_lshl_add_u64 v[34:35], s[30:31], 0, v[34:35]
	v_lshl_add_u64 v[34:35], s[50:51], 2, v[34:35]
	s_lshl_b32 s26, s66, 2
	v_lshl_add_u64 v[34:35], v[34:35], 0, s[26:27]
	global_store_dword v[34:35], v38, off
; __device__ __forceinline__ unsigned pk2(float lo, float hi) { f32x2_t v = {lo, hi}; bf16x2_t b = __builtin_convertvector(v, bf16x2_t); return __builtin_bit_cast(unsigned, b); }
; __device__ __forceinline__ float bflo(unsigned w) { return __uint_as_float(w << 16); }
; __device__ __forceinline__ float bfhi(unsigned w) { return __uint_as_float(w & 0xffff0000u); }
;     __device__ __forceinline__ void operator()(Acc& acc, const Unit& u, int wr, int wc, int fr, int fq) const {
;     ...
; #pragma unroll
;         for (int ai = 0; ai < 2; ++ai)
; #pragma unroll
;             for (int m = 0; m < 4; ++m) {
;                 const int row = u.pm * BM + ai * HALF + wr * 64 + m * 16 + fr;
;                 float ss = 0.f;
; #pragma unroll
;                 for (int bj = 0; bj < 2; ++bj) {
;                     const size_t off = (size_t)row * D + col0 + bj * HALF;
;                     f32x4 r0, r1;
;                     if (RES_BF16) { const u32x4 q = rb[ai][m][bj]; r0 = (f32x4){bflo(q.x), bfhi(q.x), bflo(q.y), bfhi(q.y)}; r1 = (f32x4){bflo(q.z), bfhi(q.z), bflo(q.w), bfhi(q.w)}; }
;                     else { r0 = *(const f32x4*)(res_f32 + off); r1 = *(const f32x4*)(res_f32 + off + 4); }
;                     const f32x4 v0 = r0 + acc[ai][bj][m][0] * alpha, v1 = r1 + acc[ai][bj][m][1] * alpha;
;                     u32x4 w; w.x = pk2(v0[0], v0[1]); w.y = pk2(v0[2], v0[3]); w.z = pk2(v1[0], v1[1]); w.w = pk2(v1[2], v1[3]);
;                     *(u32x4*)((char*)XBo + xb_piece(u.pm, u.pn, wr, wc, ai, m, bj) + xlo) = w;
;                     ss += (v0[0] * v0[0] + v0[1] * v0[1]) + (v0[2] * v0[2] + v0[3] * v0[3]) + (v1[0] * v1[0] + v1[1] * v1[1]) + (v1[2] * v1[2] + v1[3] * v1[3]);
;                 }
;                 ss += __shfl_xor(ss, 16); ss += __shfl_xor(ss, 32);
;                 if (ssqp && fq == 0) ssqp[(size_t)row * 16 + u.pn * 4 + wc] = ss;
;                 if (!RES_BF16 && (m & 1)) asm volatile("" ::: "memory");
.LBB0_555:
	s_or_b64 exec, exec, s[52:53]
	s_waitcnt vmcnt(15)
	v_lshlrev_b32_e32 v34, 16, v126
	s_waitcnt lgkmcnt(0)
	v_and_b32_e32 v35, 0xffff0000, v126
	v_lshlrev_b32_e32 v36, 16, v127
	v_and_b32_e32 v37, 0xffff0000, v127
	v_lshlrev_b32_e32 v38, 16, v128
	v_and_b32_e32 v39, 0xffff0000, v128
	v_lshlrev_b32_e32 v40, 16, v129
	v_and_b32_e32 v41, 0xffff0000, v129
	v_pk_fma_f32 v[32:33], v[32:33], 0.5, v[36:37] op_sel_hi:[1,0,1]
	v_pk_fma_f32 v[34:35], v[30:31], 0.5, v[34:35] op_sel_hi:[1,0,1]
	v_pk_fma_f32 v[36:37], v[28:29], 0.5, v[40:41] op_sel_hi:[1,0,1]
	v_pk_fma_f32 v[38:39], v[26:27], 0.5, v[38:39] op_sel_hi:[1,0,1]
	v_add_co_u32_e32 v26, vcc, s70, v158
	v_cvt_pk_bf16_f32 v28, v34, v35
	v_cvt_pk_bf16_f32 v29, v32, v33
	v_cvt_pk_bf16_f32 v30, v38, v39
	v_cvt_pk_bf16_f32 v31, v36, v37
	v_addc_co_u32_e32 v27, vcc, 0, v159, vcc
	global_store_dwordx4 v[26:27], v[28:31], off
	s_nop 1
	v_mul_f32_e32 v28, v35, v35
	v_mul_f32_e32 v29, v33, v33
	v_fmac_f32_e32 v28, v34, v34
	v_fmac_f32_e32 v29, v32, v32
	v_add_f32_e32 v28, v28, v29
	v_mul_f32_e32 v29, v39, v39
	v_fmac_f32_e32 v29, v38, v38
	v_add_f32_e32 v28, v29, v28
	v_mul_f32_e32 v29, v37, v37
	v_fmac_f32_e32 v29, v36, v36
	v_add_f32_e32 v36, v29, v28
	s_waitcnt vmcnt(15)
	v_lshlrev_b32_e32 v28, 16, v122
	v_and_b32_e32 v29, 0xffff0000, v122
	v_lshlrev_b32_e32 v30, 16, v123
	v_and_b32_e32 v31, 0xffff0000, v123
	v_pk_fma_f32 v[24:25], v[24:25], 0.5, v[30:31] op_sel_hi:[1,0,1]
	v_pk_fma_f32 v[22:23], v[22:23], 0.5, v[28:29] op_sel_hi:[1,0,1]
	v_lshlrev_b32_e32 v32, 16, v124
	v_and_b32_e32 v33, 0xffff0000, v124
	v_mul_f32_e32 v28, v23, v23
	v_mul_f32_e32 v29, v25, v25
	v_pk_fma_f32 v[18:19], v[18:19], 0.5, v[32:33] op_sel_hi:[1,0,1]
	v_fmac_f32_e32 v28, v22, v22
	v_fmac_f32_e32 v29, v24, v24
	v_lshlrev_b32_e32 v34, 16, v125
	v_and_b32_e32 v35, 0xffff0000, v125
	v_add_f32_e32 v28, v28, v29
	v_mul_f32_e32 v29, v19, v19
	v_pk_fma_f32 v[20:21], v[20:21], 0.5, v[34:35] op_sel_hi:[1,0,1]
	v_fmac_f32_e32 v29, v18, v18
	v_add_f32_e32 v28, v29, v28
	v_mul_f32_e32 v29, v21, v21
	v_fmac_f32_e32 v29, v20, v20
	v_add_f32_e32 v28, v29, v28
	v_add_f32_e32 v28, v36, v28
	ds_bpermute_b32 v29, v242, v28
	v_cvt_pk_bf16_f32 v22, v22, v23
	v_cvt_pk_bf16_f32 v23, v24, v25
	v_cvt_pk_bf16_f32 v25, v20, v21
	v_cvt_pk_bf16_f32 v24, v18, v19
	s_waitcnt lgkmcnt(0)
	v_add_f32_e32 v20, v28, v29
	ds_bpermute_b32 v21, v243, v20
	v_add_co_u32_e32 v18, vcc, s70, v130
	s_nop 1
	v_addc_co_u32_e32 v19, vcc, 0, v131, vcc
	global_store_dwordx4 v[18:19], v[22:25], off
	s_and_saveexec_b64 s[52:53], s[4:5]
	s_cbranch_execz .LBB0_557
	v_lshl_add_u32 v22, s60, 8, v236
	v_ashrrev_i32_e32 v23, 31, v22
	s_waitcnt lgkmcnt(0)
	v_add_f32_e32 v24, v20, v21
	v_lshlrev_b64 v[20:21], 6, v[22:23]
	s_ashr_i32 s51, s50, 31
	v_lshl_add_u64 v[20:21], s[30:31], 0, v[20:21]
	v_lshl_add_u64 v[20:21], s[50:51], 2, v[20:21]
	s_lshl_b32 s26, s66, 2
	v_lshl_add_u64 v[20:21], v[20:21], 0, s[26:27]
	global_store_dword v[20:21], v24, off
.LBB0_557:
	s_or_b64 exec, exec, s[52:53]
	s_waitcnt vmcnt(15)
	v_lshlrev_b32_e32 v20, 16, v110
	s_waitcnt lgkmcnt(0)
	v_and_b32_e32 v21, 0xffff0000, v110
	v_lshlrev_b32_e32 v22, 16, v111
	v_and_b32_e32 v23, 0xffff0000, v111
	v_lshlrev_b32_e32 v24, 16, v112
	v_and_b32_e32 v25, 0xffff0000, v112
	v_lshlrev_b32_e32 v28, 16, v113
	v_and_b32_e32 v29, 0xffff0000, v113
	v_pk_fma_f32 v[14:15], v[14:15], 0.5, v[20:21] op_sel_hi:[1,0,1]
	v_pk_fma_f32 v[16:17], v[16:17], 0.5, v[22:23] op_sel_hi:[1,0,1]
	v_pk_fma_f32 v[20:21], v[12:13], 0.5, v[28:29] op_sel_hi:[1,0,1]
	v_pk_fma_f32 v[12:13], v[10:11], 0.5, v[24:25] op_sel_hi:[1,0,1]
	v_cvt_pk_bf16_f32 v10, v14, v15
	v_mul_f32_e32 v15, v15, v15
	v_fmac_f32_e32 v15, v14, v14
	v_mul_f32_e32 v14, v17, v17
	v_fmac_f32_e32 v14, v16, v16
	v_add_f32_e32 v14, v15, v14
	v_mul_f32_e32 v15, v13, v13
	v_fmac_f32_e32 v15, v12, v12
	v_add_f32_e32 v14, v15, v14
	v_mul_f32_e32 v15, v21, v21
	v_fmac_f32_e32 v15, v20, v20
	v_cvt_pk_bf16_f32 v11, v16, v17
	v_add_f32_e32 v28, v15, v14
	s_waitcnt vmcnt(14)
	v_lshlrev_b32_e32 v14, 16, v98
	v_and_b32_e32 v15, 0xffff0000, v98
	v_lshlrev_b32_e32 v16, 16, v99
	v_and_b32_e32 v17, 0xffff0000, v99
	v_lshlrev_b32_e32 v22, 16, v100
	v_and_b32_e32 v23, 0xffff0000, v100
	v_pk_fma_f32 v[8:9], v[8:9], 0.5, v[16:17] op_sel_hi:[1,0,1]
	v_pk_fma_f32 v[6:7], v[6:7], 0.5, v[14:15] op_sel_hi:[1,0,1]
	v_pk_fma_f32 v[16:17], v[2:3], 0.5, v[22:23] op_sel_hi:[1,0,1]
	v_mul_f32_e32 v2, v7, v7
	v_mul_f32_e32 v3, v9, v9
	v_fmac_f32_e32 v2, v6, v6
	v_fmac_f32_e32 v3, v8, v8
	v_lshlrev_b32_e32 v24, 16, v101
	v_and_b32_e32 v25, 0xffff0000, v101
	v_add_f32_e32 v2, v2, v3
	v_mul_f32_e32 v3, v17, v17
	v_pk_fma_f32 v[14:15], v[4:5], 0.5, v[24:25] op_sel_hi:[1,0,1]
	v_fmac_f32_e32 v3, v16, v16
	v_add_f32_e32 v2, v3, v2
	v_mul_f32_e32 v3, v15, v15
	v_fmac_f32_e32 v3, v14, v14
	v_add_f32_e32 v2, v3, v2
	v_add_f32_e32 v2, v28, v2
	ds_bpermute_b32 v3, v242, v2
	v_cvt_pk_bf16_f32 v12, v12, v13
	v_cvt_pk_bf16_f32 v13, v20, v21
	v_cvt_pk_bf16_f32 v4, v6, v7
	v_cvt_pk_bf16_f32 v5, v8, v9
	s_waitcnt lgkmcnt(0)
	v_add_f32_e32 v2, v2, v3
	ds_bpermute_b32 v3, v243, v2
	v_cvt_pk_bf16_f32 v6, v16, v17
	v_cvt_pk_bf16_f32 v7, v14, v15
	global_store_dwordx4 v[26:27], v[10:13], off offset:2048
	global_store_dwordx4 v[18:19], v[4:7], off offset:2048
	s_and_saveexec_b64 s[52:53], s[4:5]
	s_cbranch_execz .LBB0_559
	v_lshl_add_u32 v4, s60, 8, v237
	v_ashrrev_i32_e32 v5, 31, v4
	s_waitcnt lgkmcnt(0)
	v_add_f32_e32 v6, v2, v3
	v_lshlrev_b64 v[2:3], 6, v[4:5]
	s_ashr_i32 s51, s50, 31
	v_lshl_add_u64 v[2:3], s[30:31], 0, v[2:3]
	v_lshl_add_u64 v[2:3], s[50:51], 2, v[2:3]
	s_lshl_b32 s26, s66, 2
	v_lshl_add_u64 v[2:3], v[2:3], 0, s[26:27]
	global_store_dword v[2:3], v6, off

; __device__ __forceinline__ unsigned pk2(float lo, float hi) { f32x2_t v = {lo, hi}; bf16x2_t b = __builtin_convertvector(v, bf16x2_t); return __builtin_bit_cast(unsigned, b); }
; __device__ __forceinline__ float bflo(unsigned w) { return __uint_as_float(w << 16); }
; __device__ __forceinline__ float bfhi(unsigned w) { return __uint_as_float(w & 0xffff0000u); }
;     __device__ __forceinline__ void operator()(Acc& acc, const Unit& u, int wr, int wc, int fr, int fq) const {
;         const int col0 = u.pn * BM + wc * 32 + 8 * fq;
;         const bf16_t* G = u.sub == 0 ? R : SS;
;         const unsigned xlo = (unsigned)lds_byte(fr, 8 * fq);
;         const size_t tbase = (size_t)u.pm * BM * D * 2; const unsigned loff = (unsigned)((wr * 64 + fr) * D + col0) * 2u;
;         const char* gbase = (const char*)G + tbase; char* obase = (char*)O + tbase;
;         u32x4 gq[2][4][2];
; #pragma unroll
;         for (int ai = 0; ai < 2; ++ai)
; #pragma unroll
;             for (int m = 0; m < 4; ++m)
; #pragma unroll
;                 for (int bj = 0; bj < 2; ++bj) gq[ai][m][bj] = *(const u32x4*)((const char*)G + ((size_t)(u.pm * 8 + 2 * u.pn + bj) << 16) + (size_t)((((wr * 4 + wc) * 8 + ai * 4 + m) << 10) + (fq * 16 + fr) * 16));
; #pragma unroll
;         for (int ai = 0; ai < 2; ++ai)
; #pragma unroll
;             for (int m = 0; m < 4; ++m) {
; #pragma unroll
;                 for (int bj = 0; bj < 2; ++bj) {
;                     const u32x4 s = gq[ai][m][bj];
;                     const float gv[8] = {bflo(s.x), bfhi(s.x), bflo(s.y), bfhi(s.y), bflo(s.z), bfhi(s.z), bflo(s.w), bfhi(s.w)};
;                     if (u.sub == 0) {
; #pragma unroll
;                         for (int j = 0; j < 4; ++j) { acc[ai][bj][m][0][j] *= gv[j]; acc[ai][bj][m][1][j] *= gv[4 + j]; }
;                     } else {
;                         float o[8];
; #pragma unroll
;                         for (int j = 0; j < 4; ++j) { o[j] = acc[ai][bj][m][0][j] * gv[j]; o[4 + j] = acc[ai][bj][m][1][j] * gv[4 + j]; }
;                         u32x4 w; w.x = pk2(o[0], o[1]); w.y = pk2(o[2], o[3]); w.z = pk2(o[4], o[5]); w.w = pk2(o[6], o[7]);
;                         *(u32x4*)((char*)O + xb_piece(u.pm, u.pn, wr, wc, ai, m, bj) + xlo) = w;
.LBB0_2108:
	s_cmp_lg_u32 s68, 0
	s_cselect_b64 s[48:49], -1, 0
	s_cmp_eq_u32 s68, 0
	s_cselect_b64 s[6:7], -1, 0
	s_and_b64 vcc, s[6:7], exec
	s_cselect_b32 s7, s9, s11
	s_cselect_b32 s6, s8, s10
	s_lshl_b32 s41, s36, 3
	s_lshl_b32 s43, s38, 1
	s_add_i32 s50, s41, s43
	s_ashr_i32 s51, s50, 31
	v_lshl_add_u64 v[4:5], s[6:7], 0, v[202:203]
	s_or_b32 s6, s50, 1
	s_lshl_b64 s[68:69], s[50:51], 16
	s_ashr_i32 s7, s6, 31
	v_lshl_add_u64 v[134:135], v[4:5], 0, s[68:69]
	s_lshl_b64 s[6:7], s[6:7], 16
	v_lshl_add_u64 v[136:137], v[4:5], 0, s[6:7]
	global_load_dwordx4 v[242:245], v[134:135], off
	global_load_dwordx4 v[186:189], v[134:135], off offset:1024
	global_load_dwordx4 v[190:193], v[136:137], off
	global_load_dwordx4 v[182:185], v[136:137], off offset:1024
	global_load_dwordx4 v[178:181], v[134:135], off offset:2048
	global_load_dwordx4 v[170:173], v[134:135], off offset:3072
	global_load_dwordx4 v[174:177], v[136:137], off offset:2048
	global_load_dwordx4 v[166:169], v[136:137], off offset:3072
	v_lshl_add_u64 v[134:135], v[4:5], 0, s[26:27]
	v_lshl_add_u64 v[136:137], v[134:135], 0, s[68:69]
	v_lshl_add_u64 v[134:135], v[134:135], 0, s[6:7]
	global_load_dwordx4 v[162:165], v[136:137], off
	global_load_dwordx4 v[158:161], v[134:135], off
	v_lshl_add_u64 v[134:135], v[4:5], 0, s[30:31]
	v_lshl_add_u64 v[136:137], v[134:135], 0, s[68:69]
	v_lshl_add_u64 v[134:135], v[134:135], 0, s[6:7]
	global_load_dwordx4 v[154:157], v[136:137], off
	global_load_dwordx4 v[150:153], v[134:135], off
	v_lshl_add_u64 v[134:135], v[4:5], 0, s[28:29]
	v_lshl_add_u64 v[136:137], v[134:135], 0, s[68:69]
	v_lshl_add_u64 v[134:135], v[134:135], 0, s[6:7]
	v_lshl_add_u64 v[4:5], v[4:5], 0, s[34:35]
	global_load_dwordx4 v[146:149], v[136:137], off
	global_load_dwordx4 v[142:145], v[134:135], off
	v_lshl_add_u64 v[134:135], v[4:5], 0, s[68:69]
	v_lshl_add_u64 v[4:5], v[4:5], 0, s[6:7]
	global_load_dwordx4 v[138:141], v[134:135], off
	s_nop 0
	global_load_dwordx4 v[134:137], v[4:5], off
	s_mov_b64 s[6:7], -1
	s_waitcnt vmcnt(15)
	v_lshlrev_b32_e32 v230, 16, v242
	v_and_b32_e32 v231, 0xffff0000, v242
	v_lshlrev_b32_e32 v228, 16, v243
	v_and_b32_e32 v229, 0xffff0000, v243
	v_lshlrev_b32_e32 v226, 16, v244
	v_and_b32_e32 v227, 0xffff0000, v244
	v_lshlrev_b32_e32 v4, 16, v245
	v_and_b32_e32 v5, 0xffff0000, v245
	s_cbranch_vccnz .LBB0_2110
	s_lshl_b32 s6, s36, 4
	s_lshl_b32 s7, s38, 2
	s_add_i32 s6, s6, s7
	s_or_b32 s6, s6, s61
	s_ashr_i32 s7, s6, 31
	v_pk_mul_f32 v[242:243], v[130:131], v[230:231]
	v_pk_mul_f32 v[244:245], v[126:127], v[226:227]
	v_pk_mul_f32 v[246:247], v[132:133], v[228:229]
	v_pk_mul_f32 v[248:249], v[128:129], v[4:5]
	s_lshl_b64 s[6:7], s[6:7], 15
	v_cvt_pk_bf16_f32 v242, v242, v243
	v_cvt_pk_bf16_f32 v243, v246, v247
	v_cvt_pk_bf16_f32 v244, v244, v245
	v_cvt_pk_bf16_f32 v245, v248, v249
	v_lshl_add_u64 v[246:247], v[204:205], 0, s[6:7]
	s_mov_b64 s[6:7], 0
	global_store_dwordx4 v[246:247], v[242:245], off

; __device__ __forceinline__ unsigned pk2(float lo, float hi) { f32x2_t v = {lo, hi}; bf16x2_t b = __builtin_convertvector(v, bf16x2_t); return __builtin_bit_cast(unsigned, b); }
; __device__ __forceinline__ float bflo(unsigned w) { return __uint_as_float(w << 16); }
; __device__ __forceinline__ float bfhi(unsigned w) { return __uint_as_float(w & 0xffff0000u); }
;     __device__ __forceinline__ void operator()(Acc& acc, const Unit& u, int wr, int wc, int fr, int fq) const {
;     ...
;                 for (int bj = 0; bj < 2; ++bj) {
;                     const u32x4 s = gq[ai][m][bj];
;                     const float gv[8] = {bflo(s.x), bfhi(s.x), bflo(s.y), bfhi(s.y), bflo(s.z), bfhi(s.z), bflo(s.w), bfhi(s.w)};
;                     if (u.sub == 0) {
; #pragma unroll
;                         for (int j = 0; j < 4; ++j) { acc[ai][bj][m][0][j] *= gv[j]; acc[ai][bj][m][1][j] *= gv[4 + j]; }
;                     } else {
;                         float o[8];
; #pragma unroll
;                         for (int j = 0; j < 4; ++j) { o[j] = acc[ai][bj][m][0][j] * gv[j]; o[4 + j] = acc[ai][bj][m][1][j] * gv[4 + j]; }
;                         u32x4 w; w.x = pk2(o[0], o[1]); w.y = pk2(o[2], o[3]); w.z = pk2(o[4], o[5]); w.w = pk2(o[6], o[7]);
;                         *(u32x4*)((char*)O + xb_piece(u.pm, u.pn, wr, wc, ai, m, bj) + xlo) = w;
;                     }
.LBB0_2112:
	v_cndmask_b32_e64 v3, 0, 1, s[48:49]
	s_waitcnt vmcnt(13)
	v_lshlrev_b32_e32 v228, 16, v190
	v_and_b32_e32 v229, 0xffff0000, v190
	v_lshlrev_b32_e32 v226, 16, v191
	v_and_b32_e32 v227, 0xffff0000, v191
	v_lshlrev_b32_e32 v190, 16, v192
	v_and_b32_e32 v191, 0xffff0000, v192
	v_lshlrev_b32_e32 v4, 16, v193
	v_and_b32_e32 v5, 0xffff0000, v193
	v_cmp_ne_u32_e64 s[6:7], 1, v3
	s_andn2_b64 vcc, exec, s[48:49]
	s_mov_b64 s[48:49], -1
	s_cbranch_vccnz .LBB0_2114
	s_lshl_b32 s41, s36, 4
	s_lshl_b32 s43, s38, 2
	s_add_i32 s41, s41, s43
	s_or_b32 s48, s41, s62
	s_ashr_i32 s49, s48, 31
	v_pk_mul_f32 v[192:193], v[98:99], v[228:229]
	v_pk_mul_f32 v[230:231], v[94:95], v[190:191]
	v_pk_mul_f32 v[244:245], v[100:101], v[226:227]
	v_pk_mul_f32 v[246:247], v[96:97], v[4:5]
	s_lshl_b64 s[48:49], s[48:49], 15
	v_cvt_pk_bf16_f32 v242, v192, v193
	v_cvt_pk_bf16_f32 v243, v244, v245
	v_cvt_pk_bf16_f32 v244, v230, v231
	v_cvt_pk_bf16_f32 v245, v246, v247
	v_lshl_add_u64 v[192:193], v[204:205], 0, s[48:49]
	s_mov_b64 s[48:49], 0
	global_store_dwordx4 v[192:193], v[242:245], off

; __device__ __forceinline__ unsigned pk2(float lo, float hi) { f32x2_t v = {lo, hi}; bf16x2_t b = __builtin_convertvector(v, bf16x2_t); return __builtin_bit_cast(unsigned, b); }
; __device__ __forceinline__ float bflo(unsigned w) { return __uint_as_float(w << 16); }
; __device__ __forceinline__ float bfhi(unsigned w) { return __uint_as_float(w & 0xffff0000u); }
;     __device__ __forceinline__ void operator()(Acc& acc, const Unit& u, int wr, int wc, int fr, int fq) const {
;     ...
;                 for (int bj = 0; bj < 2; ++bj) {
;                     const u32x4 s = gq[ai][m][bj];
;                     const float gv[8] = {bflo(s.x), bfhi(s.x), bflo(s.y), bfhi(s.y), bflo(s.z), bfhi(s.z), bflo(s.w), bfhi(s.w)};
;                     if (u.sub == 0) {
; #pragma unroll
;                         for (int j = 0; j < 4; ++j) { acc[ai][bj][m][0][j] *= gv[j]; acc[ai][bj][m][1][j] *= gv[4 + j]; }
;                     } else {
;                         float o[8];
; #pragma unroll
;                         for (int j = 0; j < 4; ++j) { o[j] = acc[ai][bj][m][0][j] * gv[j]; o[4 + j] = acc[ai][bj][m][1][j] * gv[4 + j]; }
;                         u32x4 w; w.x = pk2(o[0], o[1]); w.y = pk2(o[2], o[3]); w.z = pk2(o[4], o[5]); w.w = pk2(o[6], o[7]);
;                         *(u32x4*)((char*)O + xb_piece(u.pm, u.pn, wr, wc, ai, m, bj) + xlo) = w;
;                     }
.LBB0_2120:
	s_waitcnt vmcnt(12)
	v_lshlrev_b32_e32 v188, 16, v182
	v_and_b32_e32 v189, 0xffff0000, v182
	v_lshlrev_b32_e32 v186, 16, v183
	v_and_b32_e32 v187, 0xffff0000, v183
	v_lshlrev_b32_e32 v182, 16, v184
	v_and_b32_e32 v183, 0xffff0000, v184
	v_lshlrev_b32_e32 v4, 16, v185
	v_and_b32_e32 v5, 0xffff0000, v185
	s_and_b64 vcc, exec, s[6:7]
	s_mov_b64 s[48:49], -1
	s_cbranch_vccnz .LBB0_2122
	s_lshl_b32 s41, s36, 4
	s_lshl_b32 s43, s38, 2
	s_add_i32 s41, s41, s43
	s_or_b32 s48, s41, s62
	s_ashr_i32 s49, s48, 31
	v_pk_mul_f32 v[184:185], v[90:91], v[188:189]
	v_pk_mul_f32 v[192:193], v[86:87], v[182:183]
	v_pk_mul_f32 v[226:227], v[92:93], v[186:187]
	v_pk_mul_f32 v[228:229], v[88:89], v[4:5]
	s_lshl_b64 s[48:49], s[48:49], 15
	v_cvt_pk_bf16_f32 v190, v184, v185
	v_cvt_pk_bf16_f32 v191, v226, v227
	v_cvt_pk_bf16_f32 v192, v192, v193
	v_cvt_pk_bf16_f32 v193, v228, v229
	v_lshl_add_u64 v[184:185], v[204:205], 0, s[48:49]
	s_mov_b64 s[48:49], 0
	global_store_dwordx4 v[184:185], v[190:193], off offset:2048

; __device__ __forceinline__ unsigned pk2(float lo, float hi) { f32x2_t v = {lo, hi}; bf16x2_t b = __builtin_convertvector(v, bf16x2_t); return __builtin_bit_cast(unsigned, b); }
; __device__ __forceinline__ float bflo(unsigned w) { return __uint_as_float(w << 16); }
; __device__ __forceinline__ float bfhi(unsigned w) { return __uint_as_float(w & 0xffff0000u); }
;     __device__ __forceinline__ void operator()(Acc& acc, const Unit& u, int wr, int wc, int fr, int fq) const {
;     ...
;                 for (int bj = 0; bj < 2; ++bj) {
;                     const u32x4 s = gq[ai][m][bj];
;                     const float gv[8] = {bflo(s.x), bfhi(s.x), bflo(s.y), bfhi(s.y), bflo(s.z), bfhi(s.z), bflo(s.w), bfhi(s.w)};
;                     if (u.sub == 0) {
; #pragma unroll
;                         for (int j = 0; j < 4; ++j) { acc[ai][bj][m][0][j] *= gv[j]; acc[ai][bj][m][1][j] *= gv[4 + j]; }
;                     } else {
;                         float o[8];
; #pragma unroll
;                         for (int j = 0; j < 4; ++j) { o[j] = acc[ai][bj][m][0][j] * gv[j]; o[4 + j] = acc[ai][bj][m][1][j] * gv[4 + j]; }
;                         u32x4 w; w.x = pk2(o[0], o[1]); w.y = pk2(o[2], o[3]); w.z = pk2(o[4], o[5]); w.w = pk2(o[6], o[7]);
;                         *(u32x4*)((char*)O + xb_piece(u.pm, u.pn, wr, wc, ai, m, bj) + xlo) = w;
;                     }
.LBB0_2124:
	s_waitcnt vmcnt(11)
	v_lshlrev_b32_e32 v184, 16, v178
	v_and_b32_e32 v185, 0xffff0000, v178
	v_lshlrev_b32_e32 v182, 16, v179
	v_and_b32_e32 v183, 0xffff0000, v179
	v_lshlrev_b32_e32 v178, 16, v180
	v_and_b32_e32 v179, 0xffff0000, v180
	v_lshlrev_b32_e32 v4, 16, v181
	v_and_b32_e32 v5, 0xffff0000, v181
	s_and_b64 vcc, exec, s[6:7]
	s_mov_b64 s[48:49], -1
	s_cbranch_vccnz .LBB0_2126
	s_lshl_b32 s41, s36, 4
	s_lshl_b32 s43, s38, 2
	s_add_i32 s41, s41, s43
	s_or_b32 s48, s41, s61
	s_ashr_i32 s49, s48, 31
	v_pk_mul_f32 v[180:181], v[114:115], v[184:185]
	v_pk_mul_f32 v[188:189], v[110:111], v[178:179]
	v_pk_mul_f32 v[190:191], v[116:117], v[182:183]
	v_pk_mul_f32 v[192:193], v[112:113], v[4:5]
	s_lshl_b64 s[48:49], s[48:49], 15
	v_cvt_pk_bf16_f32 v186, v180, v181
	v_cvt_pk_bf16_f32 v187, v190, v191
	v_cvt_pk_bf16_f32 v188, v188, v189
	v_cvt_pk_bf16_f32 v189, v192, v193
	v_lshl_add_u64 v[180:181], v[206:207], 0, s[48:49]
	s_mov_b64 s[48:49], 0
	global_store_dwordx4 v[180:181], v[186:189], off

; __device__ __forceinline__ unsigned pk2(float lo, float hi) { f32x2_t v = {lo, hi}; bf16x2_t b = __builtin_convertvector(v, bf16x2_t); return __builtin_bit_cast(unsigned, b); }
; __device__ __forceinline__ float bflo(unsigned w) { return __uint_as_float(w << 16); }
; __device__ __forceinline__ float bfhi(unsigned w) { return __uint_as_float(w & 0xffff0000u); }
;     __device__ __forceinline__ void operator()(Acc& acc, const Unit& u, int wr, int wc, int fr, int fq) const {
;     ...
;                 for (int bj = 0; bj < 2; ++bj) {
;                     const u32x4 s = gq[ai][m][bj];
;                     const float gv[8] = {bflo(s.x), bfhi(s.x), bflo(s.y), bfhi(s.y), bflo(s.z), bfhi(s.z), bflo(s.w), bfhi(s.w)};
;                     if (u.sub == 0) {
; #pragma unroll
;                         for (int j = 0; j < 4; ++j) { acc[ai][bj][m][0][j] *= gv[j]; acc[ai][bj][m][1][j] *= gv[4 + j]; }
;                     } else {
;                         float o[8];
; #pragma unroll
;                         for (int j = 0; j < 4; ++j) { o[j] = acc[ai][bj][m][0][j] * gv[j]; o[4 + j] = acc[ai][bj][m][1][j] * gv[4 + j]; }
;                         u32x4 w; w.x = pk2(o[0], o[1]); w.y = pk2(o[2], o[3]); w.z = pk2(o[4], o[5]); w.w = pk2(o[6], o[7]);
;                         *(u32x4*)((char*)O + xb_piece(u.pm, u.pn, wr, wc, ai, m, bj) + xlo) = w;
;                     }
.LBB0_2128:
	s_waitcnt vmcnt(9)
	v_lshlrev_b32_e32 v180, 16, v174
	v_and_b32_e32 v181, 0xffff0000, v174
	v_lshlrev_b32_e32 v178, 16, v175
	v_and_b32_e32 v179, 0xffff0000, v175
	v_lshlrev_b32_e32 v174, 16, v176
	v_and_b32_e32 v175, 0xffff0000, v176
	v_lshlrev_b32_e32 v4, 16, v177
	v_and_b32_e32 v5, 0xffff0000, v177
	s_and_b64 vcc, exec, s[6:7]
	s_mov_b64 s[48:49], -1
	s_cbranch_vccnz .LBB0_2130
	s_lshl_b32 s41, s36, 4
	s_lshl_b32 s43, s38, 2
	s_add_i32 s41, s41, s43
	s_or_b32 s48, s41, s62
	s_ashr_i32 s49, s48, 31
	v_pk_mul_f32 v[176:177], v[82:83], v[180:181]
	v_pk_mul_f32 v[184:185], v[78:79], v[174:175]
	v_pk_mul_f32 v[186:187], v[84:85], v[178:179]
	v_pk_mul_f32 v[188:189], v[80:81], v[4:5]
	s_lshl_b64 s[48:49], s[48:49], 15
	v_cvt_pk_bf16_f32 v182, v176, v177
	v_cvt_pk_bf16_f32 v183, v186, v187
	v_cvt_pk_bf16_f32 v184, v184, v185
	v_cvt_pk_bf16_f32 v185, v188, v189
	v_lshl_add_u64 v[176:177], v[206:207], 0, s[48:49]
	s_mov_b64 s[48:49], 0
	global_store_dwordx4 v[176:177], v[182:185], off

; __device__ __forceinline__ unsigned pk2(float lo, float hi) { f32x2_t v = {lo, hi}; bf16x2_t b = __builtin_convertvector(v, bf16x2_t); return __builtin_bit_cast(unsigned, b); }
; __device__ __forceinline__ float bflo(unsigned w) { return __uint_as_float(w << 16); }
; __device__ __forceinline__ float bfhi(unsigned w) { return __uint_as_float(w & 0xffff0000u); }
;     __device__ __forceinline__ void operator()(Acc& acc, const Unit& u, int wr, int wc, int fr, int fq) const {
;     ...
;                 for (int bj = 0; bj < 2; ++bj) {
;                     const u32x4 s = gq[ai][m][bj];
;                     const float gv[8] = {bflo(s.x), bfhi(s.x), bflo(s.y), bfhi(s.y), bflo(s.z), bfhi(s.z), bflo(s.w), bfhi(s.w)};
;                     if (u.sub == 0) {
; #pragma unroll
;                         for (int j = 0; j < 4; ++j) { acc[ai][bj][m][0][j] *= gv[j]; acc[ai][bj][m][1][j] *= gv[4 + j]; }
;                     } else {
;                         float o[8];
; #pragma unroll
;                         for (int j = 0; j < 4; ++j) { o[j] = acc[ai][bj][m][0][j] * gv[j]; o[4 + j] = acc[ai][bj][m][1][j] * gv[4 + j]; }
;                         u32x4 w; w.x = pk2(o[0], o[1]); w.y = pk2(o[2], o[3]); w.z = pk2(o[4], o[5]); w.w = pk2(o[6], o[7]);
;                         *(u32x4*)((char*)O + xb_piece(u.pm, u.pn, wr, wc, ai, m, bj) + xlo) = w;
;                     }
.LBB0_2136:
	s_waitcnt vmcnt(8)
	v_lshlrev_b32_e32 v172, 16, v166
	v_and_b32_e32 v173, 0xffff0000, v166
	v_lshlrev_b32_e32 v170, 16, v167
	v_and_b32_e32 v171, 0xffff0000, v167
	v_lshlrev_b32_e32 v166, 16, v168
	v_and_b32_e32 v167, 0xffff0000, v168
	v_lshlrev_b32_e32 v4, 16, v169
	v_and_b32_e32 v5, 0xffff0000, v169
	s_and_b64 vcc, exec, s[6:7]
	s_mov_b64 s[48:49], -1
	s_cbranch_vccnz .LBB0_2138
	s_lshl_b32 s41, s36, 4
	s_lshl_b32 s43, s38, 2
	s_add_i32 s41, s41, s43
	s_or_b32 s48, s41, s62
	s_ashr_i32 s49, s48, 31
	v_pk_mul_f32 v[168:169], v[74:75], v[172:173]
	v_pk_mul_f32 v[176:177], v[70:71], v[166:167]
	v_pk_mul_f32 v[178:179], v[76:77], v[170:171]
	v_pk_mul_f32 v[180:181], v[72:73], v[4:5]
	s_lshl_b64 s[48:49], s[48:49], 15
	v_cvt_pk_bf16_f32 v174, v168, v169
	v_cvt_pk_bf16_f32 v175, v178, v179
	v_cvt_pk_bf16_f32 v176, v176, v177
	v_cvt_pk_bf16_f32 v177, v180, v181
	v_lshl_add_u64 v[168:169], v[208:209], 0, s[48:49]
	s_mov_b64 s[48:49], 0
	global_store_dwordx4 v[168:169], v[174:177], off

; __device__ __forceinline__ unsigned pk2(float lo, float hi) { f32x2_t v = {lo, hi}; bf16x2_t b = __builtin_convertvector(v, bf16x2_t); return __builtin_bit_cast(unsigned, b); }
; __device__ __forceinline__ float bflo(unsigned w) { return __uint_as_float(w << 16); }
; __device__ __forceinline__ float bfhi(unsigned w) { return __uint_as_float(w & 0xffff0000u); }
;     __device__ __forceinline__ void operator()(Acc& acc, const Unit& u, int wr, int wc, int fr, int fq) const {
;     ...
;                 for (int bj = 0; bj < 2; ++bj) {
;                     const u32x4 s = gq[ai][m][bj];
;                     const float gv[8] = {bflo(s.x), bfhi(s.x), bflo(s.y), bfhi(s.y), bflo(s.z), bfhi(s.z), bflo(s.w), bfhi(s.w)};
;                     if (u.sub == 0) {
; #pragma unroll
;                         for (int j = 0; j < 4; ++j) { acc[ai][bj][m][0][j] *= gv[j]; acc[ai][bj][m][1][j] *= gv[4 + j]; }
;                     } else {
;                         float o[8];
; #pragma unroll
;                         for (int j = 0; j < 4; ++j) { o[j] = acc[ai][bj][m][0][j] * gv[j]; o[4 + j] = acc[ai][bj][m][1][j] * gv[4 + j]; }
;                         u32x4 w; w.x = pk2(o[0], o[1]); w.y = pk2(o[2], o[3]); w.z = pk2(o[4], o[5]); w.w = pk2(o[6], o[7]);
;                         *(u32x4*)((char*)O + xb_piece(u.pm, u.pn, wr, wc, ai, m, bj) + xlo) = w;
;                     }
.LBB0_2140:
	s_waitcnt vmcnt(7)
	v_lshlrev_b32_e32 v168, 16, v162
	v_and_b32_e32 v169, 0xffff0000, v162
	v_lshlrev_b32_e32 v166, 16, v163
	v_and_b32_e32 v167, 0xffff0000, v163
	v_lshlrev_b32_e32 v162, 16, v164
	v_and_b32_e32 v163, 0xffff0000, v164
	v_lshlrev_b32_e32 v4, 16, v165
	v_and_b32_e32 v5, 0xffff0000, v165
	s_and_b64 vcc, exec, s[6:7]
	s_mov_b64 s[48:49], -1
	s_cbranch_vccnz .LBB0_2142
	s_lshl_b32 s41, s36, 4
	s_lshl_b32 s43, s38, 2
	s_add_i32 s41, s41, s43
	s_or_b32 s48, s41, s61
	s_ashr_i32 s49, s48, 31
	v_pk_mul_f32 v[164:165], v[66:67], v[168:169]
	v_pk_mul_f32 v[172:173], v[62:63], v[162:163]
	v_pk_mul_f32 v[174:175], v[68:69], v[166:167]
	v_pk_mul_f32 v[176:177], v[64:65], v[4:5]
	s_lshl_b64 s[48:49], s[48:49], 15
	v_cvt_pk_bf16_f32 v170, v164, v165
	v_cvt_pk_bf16_f32 v171, v174, v175
	v_cvt_pk_bf16_f32 v172, v172, v173
	v_cvt_pk_bf16_f32 v173, v176, v177
	v_lshl_add_u64 v[164:165], v[210:211], 0, s[48:49]
	s_mov_b64 s[48:49], 0
	global_store_dwordx4 v[164:165], v[170:173], off

; __device__ __forceinline__ unsigned pk2(float lo, float hi) { f32x2_t v = {lo, hi}; bf16x2_t b = __builtin_convertvector(v, bf16x2_t); return __builtin_bit_cast(unsigned, b); }
; __device__ __forceinline__ float bflo(unsigned w) { return __uint_as_float(w << 16); }
; __device__ __forceinline__ float bfhi(unsigned w) { return __uint_as_float(w & 0xffff0000u); }
;     __device__ __forceinline__ void operator()(Acc& acc, const Unit& u, int wr, int wc, int fr, int fq) const {
;     ...
;                 for (int bj = 0; bj < 2; ++bj) {
;                     const u32x4 s = gq[ai][m][bj];
;                     const float gv[8] = {bflo(s.x), bfhi(s.x), bflo(s.y), bfhi(s.y), bflo(s.z), bfhi(s.z), bflo(s.w), bfhi(s.w)};
;                     if (u.sub == 0) {
; #pragma unroll
;                         for (int j = 0; j < 4; ++j) { acc[ai][bj][m][0][j] *= gv[j]; acc[ai][bj][m][1][j] *= gv[4 + j]; }
;                     } else {
;                         float o[8];
; #pragma unroll
;                         for (int j = 0; j < 4; ++j) { o[j] = acc[ai][bj][m][0][j] * gv[j]; o[4 + j] = acc[ai][bj][m][1][j] * gv[4 + j]; }
;                         u32x4 w; w.x = pk2(o[0], o[1]); w.y = pk2(o[2], o[3]); w.z = pk2(o[4], o[5]); w.w = pk2(o[6], o[7]);
;                         *(u32x4*)((char*)O + xb_piece(u.pm, u.pn, wr, wc, ai, m, bj) + xlo) = w;
;                     }
.LBB0_2144:
	s_waitcnt vmcnt(6)
	v_lshlrev_b32_e32 v164, 16, v158
	v_and_b32_e32 v165, 0xffff0000, v158
	v_lshlrev_b32_e32 v162, 16, v159
	v_and_b32_e32 v163, 0xffff0000, v159
	v_lshlrev_b32_e32 v158, 16, v160
	v_and_b32_e32 v159, 0xffff0000, v160
	v_lshlrev_b32_e32 v4, 16, v161
	v_and_b32_e32 v5, 0xffff0000, v161
	s_and_b64 vcc, exec, s[6:7]
	s_mov_b64 s[48:49], -1
	s_cbranch_vccnz .LBB0_2146
	s_lshl_b32 s41, s36, 4
	s_lshl_b32 s43, s38, 2
	s_add_i32 s41, s41, s43
	s_or_b32 s48, s41, s62
	s_ashr_i32 s49, s48, 31
	v_pk_mul_f32 v[160:161], v[34:35], v[164:165]
	v_pk_mul_f32 v[168:169], v[30:31], v[158:159]
	v_pk_mul_f32 v[170:171], v[36:37], v[162:163]
	v_pk_mul_f32 v[172:173], v[32:33], v[4:5]
	s_lshl_b64 s[48:49], s[48:49], 15
	v_cvt_pk_bf16_f32 v166, v160, v161
	v_cvt_pk_bf16_f32 v167, v170, v171
	v_cvt_pk_bf16_f32 v168, v168, v169
	v_cvt_pk_bf16_f32 v169, v172, v173
	v_lshl_add_u64 v[160:161], v[210:211], 0, s[48:49]
	s_mov_b64 s[48:49], 0
	global_store_dwordx4 v[160:161], v[166:169], off

; __device__ __forceinline__ unsigned pk2(float lo, float hi) { f32x2_t v = {lo, hi}; bf16x2_t b = __builtin_convertvector(v, bf16x2_t); return __builtin_bit_cast(unsigned, b); }
; __device__ __forceinline__ float bflo(unsigned w) { return __uint_as_float(w << 16); }
; __device__ __forceinline__ float bfhi(unsigned w) { return __uint_as_float(w & 0xffff0000u); }
;     __device__ __forceinline__ void operator()(Acc& acc, const Unit& u, int wr, int wc, int fr, int fq) const {
;     ...
;                 for (int bj = 0; bj < 2; ++bj) {
;                     const u32x4 s = gq[ai][m][bj];
;                     const float gv[8] = {bflo(s.x), bfhi(s.x), bflo(s.y), bfhi(s.y), bflo(s.z), bfhi(s.z), bflo(s.w), bfhi(s.w)};
;                     if (u.sub == 0) {
; #pragma unroll
;                         for (int j = 0; j < 4; ++j) { acc[ai][bj][m][0][j] *= gv[j]; acc[ai][bj][m][1][j] *= gv[4 + j]; }
;                     } else {
;                         float o[8];
; #pragma unroll
;                         for (int j = 0; j < 4; ++j) { o[j] = acc[ai][bj][m][0][j] * gv[j]; o[4 + j] = acc[ai][bj][m][1][j] * gv[4 + j]; }
;                         u32x4 w; w.x = pk2(o[0], o[1]); w.y = pk2(o[2], o[3]); w.z = pk2(o[4], o[5]); w.w = pk2(o[6], o[7]);
;                         *(u32x4*)((char*)O + xb_piece(u.pm, u.pn, wr, wc, ai, m, bj) + xlo) = w;
;                     }
.LBB0_2148:
	s_waitcnt vmcnt(5)
	v_lshlrev_b32_e32 v160, 16, v154
	v_and_b32_e32 v161, 0xffff0000, v154
	v_lshlrev_b32_e32 v158, 16, v155
	v_and_b32_e32 v159, 0xffff0000, v155
	v_lshlrev_b32_e32 v154, 16, v156
	v_and_b32_e32 v155, 0xffff0000, v156
	v_lshlrev_b32_e32 v4, 16, v157
	v_and_b32_e32 v5, 0xffff0000, v157
	s_and_b64 vcc, exec, s[6:7]
	s_mov_b64 s[48:49], -1
	s_cbranch_vccnz .LBB0_2150
	s_lshl_b32 s41, s36, 4
	s_lshl_b32 s43, s38, 2
	s_add_i32 s41, s41, s43
	s_or_b32 s48, s41, s61
	s_ashr_i32 s49, s48, 31
	v_pk_mul_f32 v[156:157], v[58:59], v[160:161]
	v_pk_mul_f32 v[164:165], v[54:55], v[154:155]
	v_pk_mul_f32 v[166:167], v[60:61], v[158:159]
	v_pk_mul_f32 v[168:169], v[56:57], v[4:5]
	s_lshl_b64 s[48:49], s[48:49], 15
	v_cvt_pk_bf16_f32 v162, v156, v157
	v_cvt_pk_bf16_f32 v163, v166, v167
	v_cvt_pk_bf16_f32 v164, v164, v165
	v_cvt_pk_bf16_f32 v165, v168, v169
	v_lshl_add_u64 v[156:157], v[212:213], 0, s[48:49]
	s_mov_b64 s[48:49], 0
	global_store_dwordx4 v[156:157], v[162:165], off

; __device__ __forceinline__ unsigned pk2(float lo, float hi) { f32x2_t v = {lo, hi}; bf16x2_t b = __builtin_convertvector(v, bf16x2_t); return __builtin_bit_cast(unsigned, b); }
; __device__ __forceinline__ float bflo(unsigned w) { return __uint_as_float(w << 16); }
; __device__ __forceinline__ float bfhi(unsigned w) { return __uint_as_float(w & 0xffff0000u); }
;     __device__ __forceinline__ void operator()(Acc& acc, const Unit& u, int wr, int wc, int fr, int fq) const {
;     ...
;                 for (int bj = 0; bj < 2; ++bj) {
;                     const u32x4 s = gq[ai][m][bj];
;                     const float gv[8] = {bflo(s.x), bfhi(s.x), bflo(s.y), bfhi(s.y), bflo(s.z), bfhi(s.z), bflo(s.w), bfhi(s.w)};
;                     if (u.sub == 0) {
; #pragma unroll
;                         for (int j = 0; j < 4; ++j) { acc[ai][bj][m][0][j] *= gv[j]; acc[ai][bj][m][1][j] *= gv[4 + j]; }
;                     } else {
;                         float o[8];
; #pragma unroll
;                         for (int j = 0; j < 4; ++j) { o[j] = acc[ai][bj][m][0][j] * gv[j]; o[4 + j] = acc[ai][bj][m][1][j] * gv[4 + j]; }
;                         u32x4 w; w.x = pk2(o[0], o[1]); w.y = pk2(o[2], o[3]); w.z = pk2(o[4], o[5]); w.w = pk2(o[6], o[7]);
;                         *(u32x4*)((char*)O + xb_piece(u.pm, u.pn, wr, wc, ai, m, bj) + xlo) = w;
;                     }
.LBB0_2152:
	s_waitcnt vmcnt(4)
	v_lshlrev_b32_e32 v156, 16, v150
	v_and_b32_e32 v157, 0xffff0000, v150
	v_lshlrev_b32_e32 v154, 16, v151
	v_and_b32_e32 v155, 0xffff0000, v151
	v_lshlrev_b32_e32 v150, 16, v152
	v_and_b32_e32 v151, 0xffff0000, v152
	v_lshlrev_b32_e32 v4, 16, v153
	v_and_b32_e32 v5, 0xffff0000, v153
	s_and_b64 vcc, exec, s[6:7]
	s_mov_b64 s[48:49], -1
	s_cbranch_vccnz .LBB0_2154
	s_lshl_b32 s41, s36, 4
	s_lshl_b32 s43, s38, 2
	s_add_i32 s41, s41, s43
	s_or_b32 s48, s41, s62
	s_ashr_i32 s49, s48, 31
	v_pk_mul_f32 v[152:153], v[26:27], v[156:157]
	v_pk_mul_f32 v[160:161], v[22:23], v[150:151]
	v_pk_mul_f32 v[162:163], v[28:29], v[154:155]
	v_pk_mul_f32 v[164:165], v[24:25], v[4:5]
	s_lshl_b64 s[48:49], s[48:49], 15
	v_cvt_pk_bf16_f32 v158, v152, v153
	v_cvt_pk_bf16_f32 v159, v162, v163
	v_cvt_pk_bf16_f32 v160, v160, v161
	v_cvt_pk_bf16_f32 v161, v164, v165
	v_lshl_add_u64 v[152:153], v[212:213], 0, s[48:49]
	s_mov_b64 s[48:49], 0
	global_store_dwordx4 v[152:153], v[158:161], off

; __device__ __forceinline__ unsigned pk2(float lo, float hi) { f32x2_t v = {lo, hi}; bf16x2_t b = __builtin_convertvector(v, bf16x2_t); return __builtin_bit_cast(unsigned, b); }
; __device__ __forceinline__ float bflo(unsigned w) { return __uint_as_float(w << 16); }
; __device__ __forceinline__ float bfhi(unsigned w) { return __uint_as_float(w & 0xffff0000u); }
;     __device__ __forceinline__ void operator()(Acc& acc, const Unit& u, int wr, int wc, int fr, int fq) const {
;     ...
;                 for (int bj = 0; bj < 2; ++bj) {
;                     const u32x4 s = gq[ai][m][bj];
;                     const float gv[8] = {bflo(s.x), bfhi(s.x), bflo(s.y), bfhi(s.y), bflo(s.z), bfhi(s.z), bflo(s.w), bfhi(s.w)};
;                     if (u.sub == 0) {
; #pragma unroll
;                         for (int j = 0; j < 4; ++j) { acc[ai][bj][m][0][j] *= gv[j]; acc[ai][bj][m][1][j] *= gv[4 + j]; }
;                     } else {
;                         float o[8];
; #pragma unroll
;                         for (int j = 0; j < 4; ++j) { o[j] = acc[ai][bj][m][0][j] * gv[j]; o[4 + j] = acc[ai][bj][m][1][j] * gv[4 + j]; }
;                         u32x4 w; w.x = pk2(o[0], o[1]); w.y = pk2(o[2], o[3]); w.z = pk2(o[4], o[5]); w.w = pk2(o[6], o[7]);
;                         *(u32x4*)((char*)O + xb_piece(u.pm, u.pn, wr, wc, ai, m, bj) + xlo) = w;
;                     }
.LBB0_2156:
	s_waitcnt vmcnt(3)
	v_lshlrev_b32_e32 v152, 16, v146
	v_and_b32_e32 v153, 0xffff0000, v146
	v_lshlrev_b32_e32 v150, 16, v147
	v_and_b32_e32 v151, 0xffff0000, v147
	v_lshlrev_b32_e32 v146, 16, v148
	v_and_b32_e32 v147, 0xffff0000, v148
	v_lshlrev_b32_e32 v4, 16, v149
	v_and_b32_e32 v5, 0xffff0000, v149
	s_and_b64 vcc, exec, s[6:7]
	s_mov_b64 s[48:49], -1
	s_cbranch_vccnz .LBB0_2158
	s_lshl_b32 s41, s36, 4
	s_lshl_b32 s43, s38, 2
	s_add_i32 s41, s41, s43
	s_or_b32 s48, s41, s61
	s_ashr_i32 s49, s48, 31
	v_pk_mul_f32 v[148:149], v[50:51], v[152:153]
	v_pk_mul_f32 v[156:157], v[46:47], v[146:147]
	v_pk_mul_f32 v[158:159], v[52:53], v[150:151]
	v_pk_mul_f32 v[160:161], v[48:49], v[4:5]
	s_lshl_b64 s[48:49], s[48:49], 15
	v_cvt_pk_bf16_f32 v154, v148, v149
	v_cvt_pk_bf16_f32 v155, v158, v159
	v_cvt_pk_bf16_f32 v156, v156, v157
	v_cvt_pk_bf16_f32 v157, v160, v161
	v_lshl_add_u64 v[148:149], v[214:215], 0, s[48:49]
	s_mov_b64 s[48:49], 0
	global_store_dwordx4 v[148:149], v[154:157], off

; __device__ __forceinline__ unsigned pk2(float lo, float hi) { f32x2_t v = {lo, hi}; bf16x2_t b = __builtin_convertvector(v, bf16x2_t); return __builtin_bit_cast(unsigned, b); }
; __device__ __forceinline__ float bflo(unsigned w) { return __uint_as_float(w << 16); }
; __device__ __forceinline__ float bfhi(unsigned w) { return __uint_as_float(w & 0xffff0000u); }
;     __device__ __forceinline__ void operator()(Acc& acc, const Unit& u, int wr, int wc, int fr, int fq) const {
;     ...
;                 for (int bj = 0; bj < 2; ++bj) {
;                     const u32x4 s = gq[ai][m][bj];
;                     const float gv[8] = {bflo(s.x), bfhi(s.x), bflo(s.y), bfhi(s.y), bflo(s.z), bfhi(s.z), bflo(s.w), bfhi(s.w)};
;                     if (u.sub == 0) {
; #pragma unroll
;                         for (int j = 0; j < 4; ++j) { acc[ai][bj][m][0][j] *= gv[j]; acc[ai][bj][m][1][j] *= gv[4 + j]; }
;                     } else {
;                         float o[8];
; #pragma unroll
;                         for (int j = 0; j < 4; ++j) { o[j] = acc[ai][bj][m][0][j] * gv[j]; o[4 + j] = acc[ai][bj][m][1][j] * gv[4 + j]; }
;                         u32x4 w; w.x = pk2(o[0], o[1]); w.y = pk2(o[2], o[3]); w.z = pk2(o[4], o[5]); w.w = pk2(o[6], o[7]);
;                         *(u32x4*)((char*)O + xb_piece(u.pm, u.pn, wr, wc, ai, m, bj) + xlo) = w;
;                     }
.LBB0_2160:
	s_waitcnt vmcnt(2)
	v_lshlrev_b32_e32 v148, 16, v142
	v_and_b32_e32 v149, 0xffff0000, v142
	v_lshlrev_b32_e32 v146, 16, v143
	v_and_b32_e32 v147, 0xffff0000, v143
	v_lshlrev_b32_e32 v142, 16, v144
	v_and_b32_e32 v143, 0xffff0000, v144
	v_lshlrev_b32_e32 v4, 16, v145
	v_and_b32_e32 v5, 0xffff0000, v145
	s_and_b64 vcc, exec, s[6:7]
	s_mov_b64 s[48:49], -1
	s_cbranch_vccnz .LBB0_2162
	s_lshl_b32 s41, s36, 4
	s_lshl_b32 s43, s38, 2
	s_add_i32 s41, s41, s43
	s_or_b32 s48, s41, s62
	s_ashr_i32 s49, s48, 31
	v_pk_mul_f32 v[144:145], v[18:19], v[148:149]
	v_pk_mul_f32 v[152:153], v[14:15], v[142:143]
	v_pk_mul_f32 v[154:155], v[20:21], v[146:147]
	v_pk_mul_f32 v[156:157], v[16:17], v[4:5]
	s_lshl_b64 s[48:49], s[48:49], 15
	v_cvt_pk_bf16_f32 v150, v144, v145
	v_cvt_pk_bf16_f32 v151, v154, v155
	v_cvt_pk_bf16_f32 v152, v152, v153
	v_cvt_pk_bf16_f32 v153, v156, v157
	v_lshl_add_u64 v[144:145], v[214:215], 0, s[48:49]
	s_mov_b64 s[48:49], 0
	global_store_dwordx4 v[144:145], v[150:153], off

; __device__ __forceinline__ unsigned pk2(float lo, float hi) { f32x2_t v = {lo, hi}; bf16x2_t b = __builtin_convertvector(v, bf16x2_t); return __builtin_bit_cast(unsigned, b); }
; __device__ __forceinline__ float bflo(unsigned w) { return __uint_as_float(w << 16); }
; __device__ __forceinline__ float bfhi(unsigned w) { return __uint_as_float(w & 0xffff0000u); }
;     __device__ __forceinline__ void operator()(Acc& acc, const Unit& u, int wr, int wc, int fr, int fq) const {
;     ...
;                 for (int bj = 0; bj < 2; ++bj) {
;                     const u32x4 s = gq[ai][m][bj];
;                     const float gv[8] = {bflo(s.x), bfhi(s.x), bflo(s.y), bfhi(s.y), bflo(s.z), bfhi(s.z), bflo(s.w), bfhi(s.w)};
;                     if (u.sub == 0) {
; #pragma unroll
;                         for (int j = 0; j < 4; ++j) { acc[ai][bj][m][0][j] *= gv[j]; acc[ai][bj][m][1][j] *= gv[4 + j]; }
;                     } else {
;                         float o[8];
; #pragma unroll
;                         for (int j = 0; j < 4; ++j) { o[j] = acc[ai][bj][m][0][j] * gv[j]; o[4 + j] = acc[ai][bj][m][1][j] * gv[4 + j]; }
;                         u32x4 w; w.x = pk2(o[0], o[1]); w.y = pk2(o[2], o[3]); w.z = pk2(o[4], o[5]); w.w = pk2(o[6], o[7]);
;                         *(u32x4*)((char*)O + xb_piece(u.pm, u.pn, wr, wc, ai, m, bj) + xlo) = w;
;                     }
.LBB0_2164:
	s_waitcnt vmcnt(1)
	v_lshlrev_b32_e32 v144, 16, v138
	v_and_b32_e32 v145, 0xffff0000, v138
	v_lshlrev_b32_e32 v142, 16, v139
	v_and_b32_e32 v143, 0xffff0000, v139
	v_lshlrev_b32_e32 v138, 16, v140
	v_and_b32_e32 v139, 0xffff0000, v140
	v_lshlrev_b32_e32 v4, 16, v141
	v_and_b32_e32 v5, 0xffff0000, v141
	s_and_b64 vcc, exec, s[6:7]
	s_mov_b64 s[48:49], -1
	s_cbranch_vccnz .LBB0_2166
	s_lshl_b32 s41, s36, 4
	s_lshl_b32 s43, s38, 2
	s_add_i32 s41, s41, s43
	s_or_b32 s48, s41, s61
	s_ashr_i32 s49, s48, 31
	v_pk_mul_f32 v[140:141], v[42:43], v[144:145]
	v_pk_mul_f32 v[148:149], v[38:39], v[138:139]
	v_pk_mul_f32 v[150:151], v[44:45], v[142:143]
	v_pk_mul_f32 v[152:153], v[40:41], v[4:5]
	s_lshl_b64 s[48:49], s[48:49], 15
	v_cvt_pk_bf16_f32 v146, v140, v141
	v_cvt_pk_bf16_f32 v147, v150, v151
	v_cvt_pk_bf16_f32 v148, v148, v149
	v_cvt_pk_bf16_f32 v149, v152, v153
	v_lshl_add_u64 v[140:141], v[216:217], 0, s[48:49]
	s_mov_b64 s[48:49], 0
	global_store_dwordx4 v[140:141], v[146:149], off

; __device__ __forceinline__ unsigned pk2(float lo, float hi) { f32x2_t v = {lo, hi}; bf16x2_t b = __builtin_convertvector(v, bf16x2_t); return __builtin_bit_cast(unsigned, b); }
; __device__ __forceinline__ float bflo(unsigned w) { return __uint_as_float(w << 16); }
; __device__ __forceinline__ float bfhi(unsigned w) { return __uint_as_float(w & 0xffff0000u); }
;     __device__ __forceinline__ void operator()(Acc& acc, const Unit& u, int wr, int wc, int fr, int fq) const {
;     ...
;                 for (int bj = 0; bj < 2; ++bj) {
;                     const u32x4 s = gq[ai][m][bj];
;                     const float gv[8] = {bflo(s.x), bfhi(s.x), bflo(s.y), bfhi(s.y), bflo(s.z), bfhi(s.z), bflo(s.w), bfhi(s.w)};
;                     if (u.sub == 0) {
; #pragma unroll
;                         for (int j = 0; j < 4; ++j) { acc[ai][bj][m][0][j] *= gv[j]; acc[ai][bj][m][1][j] *= gv[4 + j]; }
;                     } else {
;                         float o[8];
; #pragma unroll
;                         for (int j = 0; j < 4; ++j) { o[j] = acc[ai][bj][m][0][j] * gv[j]; o[4 + j] = acc[ai][bj][m][1][j] * gv[4 + j]; }
;                         u32x4 w; w.x = pk2(o[0], o[1]); w.y = pk2(o[2], o[3]); w.z = pk2(o[4], o[5]); w.w = pk2(o[6], o[7]);
;                         *(u32x4*)((char*)O + xb_piece(u.pm, u.pn, wr, wc, ai, m, bj) + xlo) = w;
;                     }
.LBB0_2168:
	s_waitcnt vmcnt(0)
	v_lshlrev_b32_e32 v140, 16, v134
	v_and_b32_e32 v141, 0xffff0000, v134
	v_lshlrev_b32_e32 v138, 16, v135
	v_and_b32_e32 v139, 0xffff0000, v135
	v_lshlrev_b32_e32 v134, 16, v136
	v_and_b32_e32 v135, 0xffff0000, v136
	v_lshlrev_b32_e32 v4, 16, v137
	v_and_b32_e32 v5, 0xffff0000, v137
	s_and_b64 vcc, exec, s[6:7]
	s_mov_b64 s[48:49], -1
	s_cbranch_vccnz .LBB0_2171
	s_lshl_b32 s36, s36, 4
	s_lshl_b32 s38, s38, 2
	s_add_i32 s36, s36, s38
	s_or_b32 s48, s36, s62
	s_ashr_i32 s49, s48, 31
	v_pk_mul_f32 v[136:137], v[10:11], v[140:141]
	v_pk_mul_f32 v[144:145], v[6:7], v[134:135]
	v_pk_mul_f32 v[146:147], v[12:13], v[138:139]
	v_pk_mul_f32 v[148:149], v[8:9], v[4:5]
	s_lshl_b64 s[48:49], s[48:49], 15
	v_cvt_pk_bf16_f32 v142, v136, v137
	v_cvt_pk_bf16_f32 v143, v146, v147
	v_cvt_pk_bf16_f32 v144, v144, v145
	v_cvt_pk_bf16_f32 v145, v148, v149
	v_lshl_add_u64 v[136:137], v[216:217], 0, s[48:49]
	global_store_dwordx4 v[136:137], v[142:145], off
	s_cbranch_execz .LBB0_2172

; __device__ __forceinline__ unsigned pk2(float lo, float hi) { f32x2_t v = {lo, hi}; bf16x2_t b = __builtin_convertvector(v, bf16x2_t); return __builtin_bit_cast(unsigned, b); }
; __device__ __forceinline__ float bflo(unsigned w) { return __uint_as_float(w << 16); }
; __device__ __forceinline__ float bfhi(unsigned w) { return __uint_as_float(w & 0xffff0000u); }
;     __device__ __forceinline__ void operator()(Acc& acc, const Unit& u, int wr, int wc, int fr, int fq) const {
;     ...
;         u32x4 rb[2][4][2];
;         if (RES_BF16) {
; #pragma unroll
;             for (int ai = 0; ai < 2; ++ai)
; #pragma unroll
;                 for (int m = 0; m < 4; ++m)
; #pragma unroll
;                     for (int bj = 0; bj < 2; ++bj) rb[ai][m][bj] = *(const u32x4*)((const char*)XBo + xb_piece(u.pm, u.pn, wr, wc, ai, m, bj) + xlo);
;         }
; #pragma unroll
;         for (int ai = 0; ai < 2; ++ai)
; #pragma unroll
;             for (int m = 0; m < 4; ++m) {
;                 const int row = u.pm * BM + ai * HALF + wr * 64 + m * 16 + fr;
;                 float ss = 0.f;
; #pragma unroll
;                 for (int bj = 0; bj < 2; ++bj) {
;                     const size_t off = (size_t)row * D + col0 + bj * HALF;
;                     f32x4 r0, r1;
;                     if (RES_BF16) { const u32x4 q = rb[ai][m][bj]; r0 = (f32x4){bflo(q.x), bfhi(q.x), bflo(q.y), bfhi(q.y)}; r1 = (f32x4){bflo(q.z), bfhi(q.z), bflo(q.w), bfhi(q.w)}; }
;                     else { r0 = *(const f32x4*)(res_f32 + off); r1 = *(const f32x4*)(res_f32 + off + 4); }
;                     const f32x4 v0 = r0 + acc[ai][bj][m][0] * alpha, v1 = r1 + acc[ai][bj][m][1] * alpha;
;                     u32x4 w; w.x = pk2(v0[0], v0[1]); w.y = pk2(v0[2], v0[3]); w.z = pk2(v1[0], v1[1]); w.w = pk2(v1[2], v1[3]);
;                     *(u32x4*)((char*)XBo + xb_piece(u.pm, u.pn, wr, wc, ai, m, bj) + xlo) = w;
;                     ss += (v0[0] * v0[0] + v0[1] * v0[1]) + (v0[2] * v0[2] + v0[3] * v0[3]) + (v1[0] * v1[0] + v1[1] * v1[1]) + (v1[2] * v1[2] + v1[3] * v1[3]);
;                 }
;                 ss += __shfl_xor(ss, 16); ss += __shfl_xor(ss, 32);
;                 if (ssqp && fq == 0) ssqp[(size_t)row * 16 + u.pn * 4 + wc] = ss;
;                 if (!RES_BF16 && (m & 1)) asm volatile("" ::: "memory");
.LBB0_2292:
	s_lshl_b32 s49, s8, 4
	s_lshl_b32 s56, s26, 2
	s_add_i32 s49, s49, s56
	s_or_b32 s58, s49, s73
	s_ashr_i32 s59, s58, 31
	s_lshl_b64 s[60:61], s[58:59], 15
	s_or_b32 s58, s58, 2
	s_ashr_i32 s59, s58, 31
	v_lshl_add_u64 v[102:103], v[194:195], 0, s[60:61]
	s_lshl_b64 s[58:59], s[58:59], 15
	global_load_dwordx4 v[238:241], v[102:103], off
	global_load_dwordx4 v[182:185], v[102:103], off offset:2048
	v_lshl_add_u64 v[104:105], v[194:195], 0, s[58:59]
	global_load_dwordx4 v[242:245], v[104:105], off
	v_lshl_add_u64 v[110:111], v[196:197], 0, s[60:61]
	v_lshl_add_u64 v[112:113], v[198:199], 0, s[60:61]
	v_lshl_add_u64 v[122:123], v[200:201], 0, s[60:61]
	v_lshl_add_u64 v[124:125], v[202:203], 0, s[60:61]
	v_lshl_add_u64 v[134:135], v[204:205], 0, s[60:61]
	v_lshl_add_u64 v[102:103], v[196:197], 0, s[58:59]
	v_lshl_add_u64 v[136:137], v[198:199], 0, s[58:59]
	v_lshl_add_u64 v[146:147], v[200:201], 0, s[58:59]
	v_lshl_add_u64 v[148:149], v[202:203], 0, s[58:59]
	v_lshl_add_u64 v[212:213], v[206:207], 0, s[60:61]
	v_lshl_add_u64 v[236:237], v[204:205], 0, s[58:59]
	v_lshl_add_u64 v[246:247], v[206:207], 0, s[58:59]
	global_load_dwordx4 v[178:181], v[104:105], off offset:2048
	global_load_dwordx4 v[174:177], v[110:111], off
	global_load_dwordx4 v[170:173], v[102:103], off
	global_load_dwordx4 v[166:169], v[112:113], off
	global_load_dwordx4 v[162:165], v[136:137], off
	global_load_dwordx4 v[158:161], v[122:123], off
	global_load_dwordx4 v[154:157], v[146:147], off
	global_load_dwordx4 v[150:153], v[124:125], off
	s_nop 0
	global_load_dwordx4 v[146:149], v[148:149], off
	s_nop 0
	global_load_dwordx4 v[134:137], v[134:135], off
	s_nop 0
	global_load_dwordx4 v[122:125], v[236:237], off
	global_load_dwordx4 v[110:113], v[212:213], off
	global_load_dwordx4 v[102:105], v[246:247], off
	v_and_b32_e32 v212, 64, v235
	v_xor_b32_e32 v248, 16, v235
	v_add_u32_e32 v212, 64, v212
	s_add_u32 s49, s14, s60
	v_xor_b32_e32 v213, 32, v235
	v_cmp_lt_i32_e32 vcc, v248, v212
	s_addc_u32 s51, s15, s61
	s_add_u32 s60, s49, s42
	v_cndmask_b32_e32 v236, v235, v248, vcc
	v_cmp_lt_i32_e32 vcc, v213, v212
	s_addc_u32 s61, s51, s43
	v_lshlrev_b32_e32 v237, 2, v236
	v_cndmask_b32_e32 v212, v235, v213, vcc
	v_lshlrev_b32_e32 v236, 2, v212
	v_lshl_add_u64 v[212:213], s[60:61], 0, v[192:193]
	s_add_u32 s60, s14, s58
	s_addc_u32 s61, s15, s59
	s_add_u32 s58, s60, s42
	s_addc_u32 s59, s61, s43
	s_waitcnt vmcnt(15)
	v_lshlrev_b32_e32 v246, 16, v238
	v_and_b32_e32 v247, 0xffff0000, v238
	v_lshlrev_b32_e32 v238, 16, v239
	v_and_b32_e32 v239, 0xffff0000, v239
	v_lshlrev_b32_e32 v248, 16, v240
	v_and_b32_e32 v249, 0xffff0000, v240
	v_lshlrev_b32_e32 v240, 16, v241
	v_and_b32_e32 v241, 0xffff0000, v241
	v_pk_add_f32 v[144:145], v[144:145], v[238:239]
	v_pk_add_f32 v[142:143], v[142:143], v[246:247]
	v_pk_add_f32 v[238:239], v[140:141], v[240:241]
	v_pk_add_f32 v[240:241], v[138:139], v[248:249]
	s_waitcnt vmcnt(13)
	v_lshlrev_b32_e32 v246, 16, v242
	v_and_b32_e32 v247, 0xffff0000, v242
	v_lshlrev_b32_e32 v242, 16, v243
	v_and_b32_e32 v243, 0xffff0000, v243
	v_cvt_pk_bf16_f32 v138, v142, v143
	v_cvt_pk_bf16_f32 v139, v144, v145
	v_cvt_pk_bf16_f32 v140, v240, v241
	v_cvt_pk_bf16_f32 v141, v238, v239
	v_pk_add_f32 v[132:133], v[132:133], v[242:243]
	v_pk_add_f32 v[242:243], v[130:131], v[246:247]
	v_lshlrev_b32_e32 v248, 16, v244
	v_and_b32_e32 v249, 0xffff0000, v244
	global_store_dwordx4 v[212:213], v[138:141], off
	v_cvt_pk_bf16_f32 v131, v132, v133
	v_mul_f32_e32 v133, v133, v133
	v_mul_f32_e32 v139, v243, v243
	v_pk_add_f32 v[126:127], v[126:127], v[248:249]
	v_fmac_f32_e32 v139, v242, v242
	v_fmac_f32_e32 v133, v132, v132
	v_lshlrev_b32_e32 v244, 16, v245
	v_and_b32_e32 v245, 0xffff0000, v245
	v_mul_f32_e32 v143, v143, v143
	v_mul_f32_e32 v145, v145, v145
	v_add_f32_e32 v132, v139, v133
	v_mul_f32_e32 v133, v127, v127
	v_mul_f32_e32 v241, v241, v241
	v_pk_add_f32 v[128:129], v[128:129], v[244:245]
	v_fmac_f32_e32 v143, v142, v142
	v_fmac_f32_e32 v145, v144, v144
	v_fmac_f32_e32 v133, v126, v126
	v_mul_f32_e32 v239, v239, v239
	v_fmac_f32_e32 v241, v240, v240
	v_add_f32_e32 v130, v143, v145
	v_add_f32_e32 v132, v133, v132
	v_mul_f32_e32 v133, v129, v129
	v_fmac_f32_e32 v239, v238, v238
	v_add_f32_e32 v130, v241, v130
	v_fmac_f32_e32 v133, v128, v128
	v_add_f32_e32 v138, v239, v130
	v_add_f32_e32 v132, v133, v132
	v_add_f32_e32 v138, v138, v132
	ds_bpermute_b32 v139, v237, v138
	v_cvt_pk_bf16_f32 v133, v128, v129
	v_cvt_pk_bf16_f32 v130, v242, v243
	v_cvt_pk_bf16_f32 v132, v126, v127
	v_lshl_add_u64 v[126:127], s[58:59], 0, v[192:193]
	s_waitcnt lgkmcnt(0)
	v_add_f32_e32 v128, v138, v139
	ds_bpermute_b32 v129, v236, v128
	global_store_dwordx4 v[126:127], v[130:133], off
	s_and_saveexec_b64 s[58:59], s[4:5]
	s_cbranch_execz .LBB0_2294
	v_lshl_add_u32 v130, s8, 8, v223
	v_ashrrev_i32_e32 v131, 31, v130
	s_waitcnt lgkmcnt(0)
	v_add_f32_e32 v132, v128, v129
	v_lshlrev_b64 v[128:129], 6, v[130:131]
	s_ashr_i32 s57, s56, 31
	v_lshl_add_u64 v[128:129], s[30:31], 0, v[128:129]
	v_lshl_add_u64 v[128:129], s[56:57], 2, v[128:129]
	s_lshl_b32 s26, s70, 2
	v_lshl_add_u64 v[128:129], v[128:129], 0, s[26:27]
	global_store_dword v[128:129], v132, off
; __device__ __forceinline__ unsigned pk2(float lo, float hi) { f32x2_t v = {lo, hi}; bf16x2_t b = __builtin_convertvector(v, bf16x2_t); return __builtin_bit_cast(unsigned, b); }
; __device__ __forceinline__ float bflo(unsigned w) { return __uint_as_float(w << 16); }
; __device__ __forceinline__ float bfhi(unsigned w) { return __uint_as_float(w & 0xffff0000u); }
;     __device__ __forceinline__ void operator()(Acc& acc, const Unit& u, int wr, int wc, int fr, int fq) const {
;     ...
; #pragma unroll
;         for (int ai = 0; ai < 2; ++ai)
; #pragma unroll
;             for (int m = 0; m < 4; ++m) {
;                 const int row = u.pm * BM + ai * HALF + wr * 64 + m * 16 + fr;
;                 float ss = 0.f;
; #pragma unroll
;                 for (int bj = 0; bj < 2; ++bj) {
;                     const size_t off = (size_t)row * D + col0 + bj * HALF;
;                     f32x4 r0, r1;
;                     if (RES_BF16) { const u32x4 q = rb[ai][m][bj]; r0 = (f32x4){bflo(q.x), bfhi(q.x), bflo(q.y), bfhi(q.y)}; r1 = (f32x4){bflo(q.z), bfhi(q.z), bflo(q.w), bfhi(q.w)}; }
;                     else { r0 = *(const f32x4*)(res_f32 + off); r1 = *(const f32x4*)(res_f32 + off + 4); }
;                     const f32x4 v0 = r0 + acc[ai][bj][m][0] * alpha, v1 = r1 + acc[ai][bj][m][1] * alpha;
;                     u32x4 w; w.x = pk2(v0[0], v0[1]); w.y = pk2(v0[2], v0[3]); w.z = pk2(v1[0], v1[1]); w.w = pk2(v1[2], v1[3]);
;                     *(u32x4*)((char*)XBo + xb_piece(u.pm, u.pn, wr, wc, ai, m, bj) + xlo) = w;
;                     ss += (v0[0] * v0[0] + v0[1] * v0[1]) + (v0[2] * v0[2] + v0[3] * v0[3]) + (v1[0] * v1[0] + v1[1] * v1[1]) + (v1[2] * v1[2] + v1[3] * v1[3]);
;                 }
;                 ss += __shfl_xor(ss, 16); ss += __shfl_xor(ss, 32);
;                 if (ssqp && fq == 0) ssqp[(size_t)row * 16 + u.pn * 4 + wc] = ss;
;                 if (!RES_BF16 && (m & 1)) asm volatile("" ::: "memory");
.LBB0_2294:
	s_or_b64 exec, exec, s[58:59]
	v_lshlrev_b32_e32 v128, 16, v182
	s_waitcnt lgkmcnt(0)
	v_and_b32_e32 v129, 0xffff0000, v182
	v_lshlrev_b32_e32 v130, 16, v183
	v_and_b32_e32 v131, 0xffff0000, v183
	v_lshlrev_b32_e32 v132, 16, v184
	v_and_b32_e32 v133, 0xffff0000, v184
	v_lshlrev_b32_e32 v138, 16, v185
	v_and_b32_e32 v139, 0xffff0000, v185
	v_pk_add_f32 v[118:119], v[118:119], v[128:129]
	v_pk_add_f32 v[120:121], v[120:121], v[130:131]
	v_pk_add_f32 v[128:129], v[116:117], v[138:139]
	v_pk_add_f32 v[116:117], v[114:115], v[132:133]
	v_cvt_pk_bf16_f32 v114, v118, v119
	v_mul_f32_e32 v119, v119, v119
	v_fmac_f32_e32 v119, v118, v118
	v_mul_f32_e32 v118, v121, v121
	v_fmac_f32_e32 v118, v120, v120
	v_add_f32_e32 v118, v119, v118
	v_mul_f32_e32 v119, v117, v117
	v_fmac_f32_e32 v119, v116, v116
	v_add_f32_e32 v118, v119, v118
	v_mul_f32_e32 v119, v129, v129
	v_fmac_f32_e32 v119, v128, v128
	v_cvt_pk_bf16_f32 v115, v120, v121
	v_add_f32_e32 v138, v119, v118
	s_waitcnt vmcnt(14)
	v_lshlrev_b32_e32 v118, 16, v178
	v_and_b32_e32 v119, 0xffff0000, v178
	v_lshlrev_b32_e32 v120, 16, v179
	v_and_b32_e32 v121, 0xffff0000, v179
	v_lshlrev_b32_e32 v130, 16, v180
	v_and_b32_e32 v131, 0xffff0000, v180
	v_pk_add_f32 v[108:109], v[108:109], v[120:121]
	v_pk_add_f32 v[106:107], v[106:107], v[118:119]
	v_pk_add_f32 v[118:119], v[98:99], v[130:131]
	v_mul_f32_e32 v98, v107, v107
	v_mul_f32_e32 v99, v109, v109
	v_fmac_f32_e32 v98, v106, v106
	v_fmac_f32_e32 v99, v108, v108
	v_lshlrev_b32_e32 v132, 16, v181
	v_and_b32_e32 v133, 0xffff0000, v181
	v_add_f32_e32 v98, v98, v99
	v_mul_f32_e32 v99, v119, v119
	v_pk_add_f32 v[100:101], v[100:101], v[132:133]
	v_fmac_f32_e32 v99, v118, v118
	v_add_f32_e32 v98, v99, v98
	v_mul_f32_e32 v99, v101, v101
	v_fmac_f32_e32 v99, v100, v100
	v_add_f32_e32 v98, v99, v98
	v_add_f32_e32 v98, v138, v98
	ds_bpermute_b32 v99, v237, v98
	v_cvt_pk_bf16_f32 v116, v116, v117
	v_cvt_pk_bf16_f32 v117, v128, v129
	v_cvt_pk_bf16_f32 v106, v106, v107
	v_cvt_pk_bf16_f32 v107, v108, v109
	s_waitcnt lgkmcnt(0)
	v_add_f32_e32 v98, v98, v99
	ds_bpermute_b32 v99, v236, v98
	v_cvt_pk_bf16_f32 v108, v118, v119
	v_cvt_pk_bf16_f32 v109, v100, v101
	global_store_dwordx4 v[212:213], v[114:117], off offset:2048
	global_store_dwordx4 v[126:127], v[106:109], off offset:2048
	s_and_saveexec_b64 s[58:59], s[4:5]
	s_cbranch_execz .LBB0_2296
	v_lshl_add_u32 v100, s8, 8, v225
	v_ashrrev_i32_e32 v101, 31, v100
	s_waitcnt lgkmcnt(0)
	v_add_f32_e32 v106, v98, v99
	v_lshlrev_b64 v[98:99], 6, v[100:101]
	s_ashr_i32 s57, s56, 31
	v_lshl_add_u64 v[98:99], s[30:31], 0, v[98:99]
	v_lshl_add_u64 v[98:99], s[56:57], 2, v[98:99]
	s_lshl_b32 s26, s70, 2
	v_lshl_add_u64 v[98:99], v[98:99], 0, s[26:27]
	global_store_dword v[98:99], v106, off
.LBB0_2296:
	s_or_b64 exec, exec, s[58:59]
	s_waitcnt vmcnt(15)
	v_lshlrev_b32_e32 v98, 16, v174
	s_waitcnt lgkmcnt(0)
	v_and_b32_e32 v99, 0xffff0000, v174
	v_lshlrev_b32_e32 v100, 16, v175
	v_and_b32_e32 v101, 0xffff0000, v175
	v_lshlrev_b32_e32 v106, 16, v176
	v_and_b32_e32 v107, 0xffff0000, v176
	v_lshlrev_b32_e32 v108, 16, v177
	v_and_b32_e32 v109, 0xffff0000, v177
	s_add_u32 s58, s49, s46
	v_pk_add_f32 v[96:97], v[96:97], v[100:101]
	v_pk_add_f32 v[94:95], v[94:95], v[98:99]
	v_pk_add_f32 v[98:99], v[92:93], v[108:109]
	v_pk_add_f32 v[100:101], v[90:91], v[106:107]
	s_addc_u32 s59, s51, s47
	v_cvt_pk_bf16_f32 v90, v94, v95
	v_cvt_pk_bf16_f32 v91, v96, v97
	v_cvt_pk_bf16_f32 v92, v100, v101
	v_cvt_pk_bf16_f32 v93, v98, v99
	v_lshl_add_u64 v[106:107], s[58:59], 0, v[192:193]
	global_store_dwordx4 v[106:107], v[90:93], off
	s_add_u32 s58, s60, s46
	s_addc_u32 s59, s61, s47
	v_mul_f32_e32 v90, v95, v95
	v_mul_f32_e32 v91, v97, v97
	v_fmac_f32_e32 v90, v94, v94
	v_fmac_f32_e32 v91, v96, v96
	v_add_f32_e32 v90, v90, v91
	v_mul_f32_e32 v91, v101, v101
	v_fmac_f32_e32 v91, v100, v100
	v_add_f32_e32 v90, v91, v90
	v_mul_f32_e32 v91, v99, v99
	v_fmac_f32_e32 v91, v98, v98
	v_add_f32_e32 v98, v91, v90
	s_waitcnt vmcnt(15)
	v_lshlrev_b32_e32 v90, 16, v170
	v_and_b32_e32 v91, 0xffff0000, v170
	v_lshlrev_b32_e32 v92, 16, v171
	v_and_b32_e32 v93, 0xffff0000, v171
	v_lshlrev_b32_e32 v96, 16, v173
	v_and_b32_e32 v97, 0xffff0000, v173
	v_pk_add_f32 v[88:89], v[88:89], v[92:93]
	v_pk_add_f32 v[86:87], v[86:87], v[90:91]
	v_lshlrev_b32_e32 v94, 16, v172
	v_and_b32_e32 v95, 0xffff0000, v172
	v_pk_add_f32 v[90:91], v[84:85], v[96:97]
	v_mul_f32_e32 v84, v87, v87
	v_mul_f32_e32 v85, v89, v89
	v_pk_add_f32 v[82:83], v[82:83], v[94:95]
	v_fmac_f32_e32 v84, v86, v86
	v_fmac_f32_e32 v85, v88, v88
	v_add_f32_e32 v84, v84, v85
	v_mul_f32_e32 v85, v83, v83
	v_fmac_f32_e32 v85, v82, v82
	v_add_f32_e32 v84, v85, v84
	v_mul_f32_e32 v85, v91, v91
	v_fmac_f32_e32 v85, v90, v90
	v_add_f32_e32 v84, v85, v84
	v_add_f32_e32 v92, v98, v84
	ds_bpermute_b32 v93, v237, v92
	v_cvt_pk_bf16_f32 v84, v86, v87
	v_cvt_pk_bf16_f32 v86, v82, v83
	v_cvt_pk_bf16_f32 v85, v88, v89
	v_cvt_pk_bf16_f32 v87, v90, v91
	s_waitcnt lgkmcnt(0)
	v_add_f32_e32 v82, v92, v93
	ds_bpermute_b32 v83, v236, v82
	v_lshl_add_u64 v[88:89], s[58:59], 0, v[192:193]
	global_store_dwordx4 v[88:89], v[84:87], off
	s_and_saveexec_b64 s[58:59], s[4:5]
	s_cbranch_execz .LBB0_2298
	v_lshl_add_u32 v84, s8, 8, v226
	v_ashrrev_i32_e32 v85, 31, v84
	s_waitcnt lgkmcnt(0)
	v_add_f32_e32 v86, v82, v83
	v_lshlrev_b64 v[82:83], 6, v[84:85]
	s_ashr_i32 s57, s56, 31
	v_lshl_add_u64 v[82:83], s[30:31], 0, v[82:83]
	v_lshl_add_u64 v[82:83], s[56:57], 2, v[82:83]
	s_lshl_b32 s26, s70, 2
	v_lshl_add_u64 v[82:83], v[82:83], 0, s[26:27]
	global_store_dword v[82:83], v86, off
; __device__ __forceinline__ unsigned pk2(float lo, float hi) { f32x2_t v = {lo, hi}; bf16x2_t b = __builtin_convertvector(v, bf16x2_t); return __builtin_bit_cast(unsigned, b); }
; __device__ __forceinline__ float bflo(unsigned w) { return __uint_as_float(w << 16); }
; __device__ __forceinline__ float bfhi(unsigned w) { return __uint_as_float(w & 0xffff0000u); }
;     __device__ __forceinline__ void operator()(Acc& acc, const Unit& u, int wr, int wc, int fr, int fq) const {
;     ...
; #pragma unroll
;         for (int ai = 0; ai < 2; ++ai)
; #pragma unroll
;             for (int m = 0; m < 4; ++m) {
;                 const int row = u.pm * BM + ai * HALF + wr * 64 + m * 16 + fr;
;                 float ss = 0.f;
; #pragma unroll
;                 for (int bj = 0; bj < 2; ++bj) {
;                     const size_t off = (size_t)row * D + col0 + bj * HALF;
;                     f32x4 r0, r1;
;                     if (RES_BF16) { const u32x4 q = rb[ai][m][bj]; r0 = (f32x4){bflo(q.x), bfhi(q.x), bflo(q.y), bfhi(q.y)}; r1 = (f32x4){bflo(q.z), bfhi(q.z), bflo(q.w), bfhi(q.w)}; }
;                     else { r0 = *(const f32x4*)(res_f32 + off); r1 = *(const f32x4*)(res_f32 + off + 4); }
;                     const f32x4 v0 = r0 + acc[ai][bj][m][0] * alpha, v1 = r1 + acc[ai][bj][m][1] * alpha;
;                     u32x4 w; w.x = pk2(v0[0], v0[1]); w.y = pk2(v0[2], v0[3]); w.z = pk2(v1[0], v1[1]); w.w = pk2(v1[2], v1[3]);
;                     *(u32x4*)((char*)XBo + xb_piece(u.pm, u.pn, wr, wc, ai, m, bj) + xlo) = w;
;                     ss += (v0[0] * v0[0] + v0[1] * v0[1]) + (v0[2] * v0[2] + v0[3] * v0[3]) + (v1[0] * v1[0] + v1[1] * v1[1]) + (v1[2] * v1[2] + v1[3] * v1[3]);
;                 }
;                 ss += __shfl_xor(ss, 16); ss += __shfl_xor(ss, 32);
;                 if (ssqp && fq == 0) ssqp[(size_t)row * 16 + u.pn * 4 + wc] = ss;
;                 if (!RES_BF16 && (m & 1)) asm volatile("" ::: "memory");
.LBB0_2298:
	s_or_b64 exec, exec, s[58:59]
	s_waitcnt vmcnt(15)
	v_lshlrev_b32_e32 v82, 16, v166
	s_waitcnt lgkmcnt(0)
	v_and_b32_e32 v83, 0xffff0000, v166
	v_lshlrev_b32_e32 v84, 16, v167
	v_and_b32_e32 v85, 0xffff0000, v167
	v_lshlrev_b32_e32 v86, 16, v168
	v_and_b32_e32 v87, 0xffff0000, v168
	v_lshlrev_b32_e32 v88, 16, v169
	v_and_b32_e32 v89, 0xffff0000, v169
	s_add_u32 s58, s49, s44
	v_pk_add_f32 v[80:81], v[80:81], v[84:85]
	v_pk_add_f32 v[78:79], v[78:79], v[82:83]
	v_pk_add_f32 v[82:83], v[76:77], v[88:89]
	v_pk_add_f32 v[84:85], v[74:75], v[86:87]
	s_addc_u32 s59, s51, s45
	v_cvt_pk_bf16_f32 v74, v78, v79
	v_cvt_pk_bf16_f32 v75, v80, v81
	v_cvt_pk_bf16_f32 v76, v84, v85
	v_cvt_pk_bf16_f32 v77, v82, v83
	v_lshl_add_u64 v[86:87], s[58:59], 0, v[192:193]
	global_store_dwordx4 v[86:87], v[74:77], off
	s_add_u32 s58, s60, s44
	s_addc_u32 s59, s61, s45
	v_mul_f32_e32 v74, v79, v79
	v_mul_f32_e32 v75, v81, v81
	v_fmac_f32_e32 v74, v78, v78
	v_fmac_f32_e32 v75, v80, v80
	v_add_f32_e32 v74, v74, v75
	v_mul_f32_e32 v75, v85, v85
	v_fmac_f32_e32 v75, v84, v84
	v_add_f32_e32 v74, v75, v74
	v_mul_f32_e32 v75, v83, v83
	v_fmac_f32_e32 v75, v82, v82
	v_add_f32_e32 v82, v75, v74
	s_waitcnt vmcnt(15)
	v_lshlrev_b32_e32 v74, 16, v162
	v_and_b32_e32 v75, 0xffff0000, v162
	v_lshlrev_b32_e32 v76, 16, v163
	v_and_b32_e32 v77, 0xffff0000, v163
	v_lshlrev_b32_e32 v80, 16, v165
	v_and_b32_e32 v81, 0xffff0000, v165
	v_pk_add_f32 v[72:73], v[72:73], v[76:77]
	v_pk_add_f32 v[70:71], v[70:71], v[74:75]
	v_lshlrev_b32_e32 v78, 16, v164
	v_and_b32_e32 v79, 0xffff0000, v164
	v_pk_add_f32 v[74:75], v[68:69], v[80:81]
	v_mul_f32_e32 v68, v71, v71
	v_mul_f32_e32 v69, v73, v73
	v_pk_add_f32 v[66:67], v[66:67], v[78:79]
	v_fmac_f32_e32 v68, v70, v70
	v_fmac_f32_e32 v69, v72, v72
	v_add_f32_e32 v68, v68, v69
	v_mul_f32_e32 v69, v67, v67
	v_fmac_f32_e32 v69, v66, v66
	v_add_f32_e32 v68, v69, v68
	v_mul_f32_e32 v69, v75, v75
	v_fmac_f32_e32 v69, v74, v74
	v_add_f32_e32 v68, v69, v68
	v_add_f32_e32 v76, v82, v68
	ds_bpermute_b32 v77, v237, v76
	v_cvt_pk_bf16_f32 v68, v70, v71
	v_cvt_pk_bf16_f32 v70, v66, v67
	v_cvt_pk_bf16_f32 v69, v72, v73
	v_cvt_pk_bf16_f32 v71, v74, v75
	s_waitcnt lgkmcnt(0)
	v_add_f32_e32 v66, v76, v77
	ds_bpermute_b32 v67, v236, v66
	v_lshl_add_u64 v[72:73], s[58:59], 0, v[192:193]
	global_store_dwordx4 v[72:73], v[68:71], off
	s_and_saveexec_b64 s[58:59], s[4:5]
	s_cbranch_execz .LBB0_2300
	v_lshl_add_u32 v68, s8, 8, v227
	v_ashrrev_i32_e32 v69, 31, v68
	s_waitcnt lgkmcnt(0)
	v_add_f32_e32 v70, v66, v67
	v_lshlrev_b64 v[66:67], 6, v[68:69]
	s_ashr_i32 s57, s56, 31
	v_lshl_add_u64 v[66:67], s[30:31], 0, v[66:67]
	v_lshl_add_u64 v[66:67], s[56:57], 2, v[66:67]
	s_lshl_b32 s26, s70, 2
	v_lshl_add_u64 v[66:67], v[66:67], 0, s[26:27]
	global_store_dword v[66:67], v70, off
.LBB0_2300:
	s_or_b64 exec, exec, s[58:59]
	s_waitcnt vmcnt(15)
	v_lshlrev_b32_e32 v66, 16, v158
	s_waitcnt lgkmcnt(0)
	v_and_b32_e32 v67, 0xffff0000, v158
	v_lshlrev_b32_e32 v68, 16, v159
	v_and_b32_e32 v69, 0xffff0000, v159
	v_lshlrev_b32_e32 v70, 16, v160
	v_and_b32_e32 v71, 0xffff0000, v160
	v_lshlrev_b32_e32 v72, 16, v161
	v_and_b32_e32 v73, 0xffff0000, v161
	v_pk_add_f32 v[64:65], v[64:65], v[68:69]
	v_pk_add_f32 v[66:67], v[62:63], v[66:67]
	v_pk_add_f32 v[68:69], v[60:61], v[72:73]
	v_pk_add_f32 v[70:71], v[58:59], v[70:71]
	v_add_co_u32_e32 v58, vcc, s69, v212
	v_cvt_pk_bf16_f32 v60, v66, v67
	v_cvt_pk_bf16_f32 v61, v64, v65
	v_cvt_pk_bf16_f32 v62, v70, v71
	v_cvt_pk_bf16_f32 v63, v68, v69
	v_addc_co_u32_e32 v59, vcc, 0, v213, vcc
	global_store_dwordx4 v[58:59], v[60:63], off
	s_nop 1
	v_mul_f32_e32 v60, v67, v67
	v_mul_f32_e32 v61, v65, v65
	v_fmac_f32_e32 v60, v66, v66
	v_fmac_f32_e32 v61, v64, v64
	v_add_f32_e32 v60, v60, v61
	v_mul_f32_e32 v61, v71, v71
	v_fmac_f32_e32 v61, v70, v70
	v_add_f32_e32 v60, v61, v60
	v_mul_f32_e32 v61, v69, v69
	v_fmac_f32_e32 v61, v68, v68
	v_add_f32_e32 v68, v61, v60
	s_waitcnt vmcnt(15)
	v_lshlrev_b32_e32 v60, 16, v154
	v_and_b32_e32 v61, 0xffff0000, v154
	v_lshlrev_b32_e32 v62, 16, v155
	v_and_b32_e32 v63, 0xffff0000, v155
	v_pk_add_f32 v[56:57], v[56:57], v[62:63]
	v_pk_add_f32 v[54:55], v[54:55], v[60:61]
	v_lshlrev_b32_e32 v64, 16, v156
	v_and_b32_e32 v65, 0xffff0000, v156
	v_mul_f32_e32 v60, v55, v55
	v_mul_f32_e32 v61, v57, v57
	v_pk_add_f32 v[50:51], v[50:51], v[64:65]
	v_fmac_f32_e32 v60, v54, v54
	v_fmac_f32_e32 v61, v56, v56
	v_lshlrev_b32_e32 v66, 16, v157
	v_and_b32_e32 v67, 0xffff0000, v157
	v_add_f32_e32 v60, v60, v61
	v_mul_f32_e32 v61, v51, v51
	v_pk_add_f32 v[52:53], v[52:53], v[66:67]
	v_fmac_f32_e32 v61, v50, v50
	v_add_f32_e32 v60, v61, v60
	v_mul_f32_e32 v61, v53, v53
	v_fmac_f32_e32 v61, v52, v52
	v_add_f32_e32 v60, v61, v60
	v_add_f32_e32 v60, v68, v60
	ds_bpermute_b32 v61, v237, v60
	v_cvt_pk_bf16_f32 v54, v54, v55
	v_cvt_pk_bf16_f32 v55, v56, v57
	v_cvt_pk_bf16_f32 v57, v52, v53
	v_cvt_pk_bf16_f32 v56, v50, v51
	s_waitcnt lgkmcnt(0)
	v_add_f32_e32 v52, v60, v61
	ds_bpermute_b32 v53, v236, v52
	v_add_co_u32_e32 v50, vcc, s69, v126
	s_nop 1
	v_addc_co_u32_e32 v51, vcc, 0, v127, vcc
	global_store_dwordx4 v[50:51], v[54:57], off
	s_and_saveexec_b64 s[58:59], s[4:5]
	s_cbranch_execz .LBB0_2302
	v_lshl_add_u32 v54, s8, 8, v228
	v_ashrrev_i32_e32 v55, 31, v54
	s_waitcnt lgkmcnt(0)
	v_add_f32_e32 v56, v52, v53
	v_lshlrev_b64 v[52:53], 6, v[54:55]
	s_ashr_i32 s57, s56, 31
	v_lshl_add_u64 v[52:53], s[30:31], 0, v[52:53]
	v_lshl_add_u64 v[52:53], s[56:57], 2, v[52:53]
	s_lshl_b32 s26, s70, 2
	v_lshl_add_u64 v[52:53], v[52:53], 0, s[26:27]
	global_store_dword v[52:53], v56, off
; __device__ __forceinline__ unsigned pk2(float lo, float hi) { f32x2_t v = {lo, hi}; bf16x2_t b = __builtin_convertvector(v, bf16x2_t); return __builtin_bit_cast(unsigned, b); }
; __device__ __forceinline__ float bflo(unsigned w) { return __uint_as_float(w << 16); }
; __device__ __forceinline__ float bfhi(unsigned w) { return __uint_as_float(w & 0xffff0000u); }
;     __device__ __forceinline__ void operator()(Acc& acc, const Unit& u, int wr, int wc, int fr, int fq) const {
;     ...
; #pragma unroll
;         for (int ai = 0; ai < 2; ++ai)
; #pragma unroll
;             for (int m = 0; m < 4; ++m) {
;                 const int row = u.pm * BM + ai * HALF + wr * 64 + m * 16 + fr;
;                 float ss = 0.f;
; #pragma unroll
;                 for (int bj = 0; bj < 2; ++bj) {
;                     const size_t off = (size_t)row * D + col0 + bj * HALF;
;                     f32x4 r0, r1;
;                     if (RES_BF16) { const u32x4 q = rb[ai][m][bj]; r0 = (f32x4){bflo(q.x), bfhi(q.x), bflo(q.y), bfhi(q.y)}; r1 = (f32x4){bflo(q.z), bfhi(q.z), bflo(q.w), bfhi(q.w)}; }
;                     else { r0 = *(const f32x4*)(res_f32 + off); r1 = *(const f32x4*)(res_f32 + off + 4); }
;                     const f32x4 v0 = r0 + acc[ai][bj][m][0] * alpha, v1 = r1 + acc[ai][bj][m][1] * alpha;
;                     u32x4 w; w.x = pk2(v0[0], v0[1]); w.y = pk2(v0[2], v0[3]); w.z = pk2(v1[0], v1[1]); w.w = pk2(v1[2], v1[3]);
;                     *(u32x4*)((char*)XBo + xb_piece(u.pm, u.pn, wr, wc, ai, m, bj) + xlo) = w;
;                     ss += (v0[0] * v0[0] + v0[1] * v0[1]) + (v0[2] * v0[2] + v0[3] * v0[3]) + (v1[0] * v1[0] + v1[1] * v1[1]) + (v1[2] * v1[2] + v1[3] * v1[3]);
;                 }
;                 ss += __shfl_xor(ss, 16); ss += __shfl_xor(ss, 32);
;                 if (ssqp && fq == 0) ssqp[(size_t)row * 16 + u.pn * 4 + wc] = ss;
;                 if (!RES_BF16 && (m & 1)) asm volatile("" ::: "memory");
.LBB0_2302:
	s_or_b64 exec, exec, s[58:59]
	s_waitcnt vmcnt(15)
	v_lshlrev_b32_e32 v52, 16, v150
	s_waitcnt lgkmcnt(0)
	v_and_b32_e32 v53, 0xffff0000, v150
	v_lshlrev_b32_e32 v54, 16, v151
	v_and_b32_e32 v55, 0xffff0000, v151
	v_lshlrev_b32_e32 v56, 16, v152
	v_and_b32_e32 v57, 0xffff0000, v152
	v_lshlrev_b32_e32 v60, 16, v153
	v_and_b32_e32 v61, 0xffff0000, v153
	v_pk_add_f32 v[46:47], v[46:47], v[52:53]
	v_pk_add_f32 v[48:49], v[48:49], v[54:55]
	v_pk_add_f32 v[52:53], v[44:45], v[60:61]
	v_pk_add_f32 v[44:45], v[42:43], v[56:57]
	v_cvt_pk_bf16_f32 v42, v46, v47
	v_mul_f32_e32 v47, v47, v47
	v_fmac_f32_e32 v47, v46, v46
	v_mul_f32_e32 v46, v49, v49
	v_fmac_f32_e32 v46, v48, v48
	v_add_f32_e32 v46, v47, v46
	v_mul_f32_e32 v47, v45, v45
	v_fmac_f32_e32 v47, v44, v44
	v_add_f32_e32 v46, v47, v46
	v_mul_f32_e32 v47, v53, v53
	v_fmac_f32_e32 v47, v52, v52
	v_cvt_pk_bf16_f32 v43, v48, v49
	v_add_f32_e32 v60, v47, v46
	s_waitcnt vmcnt(14)
	v_lshlrev_b32_e32 v46, 16, v146
	v_and_b32_e32 v47, 0xffff0000, v146
	v_lshlrev_b32_e32 v48, 16, v147
	v_and_b32_e32 v49, 0xffff0000, v147
	v_lshlrev_b32_e32 v54, 16, v148
	v_and_b32_e32 v55, 0xffff0000, v148
	v_pk_add_f32 v[40:41], v[40:41], v[48:49]
	v_pk_add_f32 v[38:39], v[38:39], v[46:47]
	v_pk_add_f32 v[48:49], v[34:35], v[54:55]
	v_mul_f32_e32 v34, v39, v39
	v_mul_f32_e32 v35, v41, v41
	v_fmac_f32_e32 v34, v38, v38
	v_fmac_f32_e32 v35, v40, v40
	v_lshlrev_b32_e32 v56, 16, v149
	v_and_b32_e32 v57, 0xffff0000, v149
	v_add_f32_e32 v34, v34, v35
	v_mul_f32_e32 v35, v49, v49
	v_pk_add_f32 v[46:47], v[36:37], v[56:57]
	v_fmac_f32_e32 v35, v48, v48
	v_add_f32_e32 v34, v35, v34
	v_mul_f32_e32 v35, v47, v47
	v_fmac_f32_e32 v35, v46, v46
	v_add_f32_e32 v34, v35, v34
	v_add_f32_e32 v34, v60, v34
	ds_bpermute_b32 v35, v237, v34
	v_cvt_pk_bf16_f32 v44, v44, v45
	v_cvt_pk_bf16_f32 v45, v52, v53
	v_cvt_pk_bf16_f32 v36, v38, v39
	v_cvt_pk_bf16_f32 v37, v40, v41
	s_waitcnt lgkmcnt(0)
	v_add_f32_e32 v34, v34, v35
	ds_bpermute_b32 v35, v236, v34
	v_cvt_pk_bf16_f32 v38, v48, v49
	v_cvt_pk_bf16_f32 v39, v46, v47
	global_store_dwordx4 v[58:59], v[42:45], off offset:2048
	global_store_dwordx4 v[50:51], v[36:39], off offset:2048
	s_and_saveexec_b64 s[58:59], s[4:5]
	s_cbranch_execz .LBB0_2304
	v_lshl_add_u32 v36, s8, 8, v229
	v_ashrrev_i32_e32 v37, 31, v36
	s_waitcnt lgkmcnt(0)
	v_add_f32_e32 v38, v34, v35
	v_lshlrev_b64 v[34:35], 6, v[36:37]
	s_ashr_i32 s57, s56, 31
	v_lshl_add_u64 v[34:35], s[30:31], 0, v[34:35]
	v_lshl_add_u64 v[34:35], s[56:57], 2, v[34:35]
	s_lshl_b32 s26, s70, 2
	v_lshl_add_u64 v[34:35], v[34:35], 0, s[26:27]
	global_store_dword v[34:35], v38, off
; __device__ __forceinline__ unsigned pk2(float lo, float hi) { f32x2_t v = {lo, hi}; bf16x2_t b = __builtin_convertvector(v, bf16x2_t); return __builtin_bit_cast(unsigned, b); }
; __device__ __forceinline__ float bflo(unsigned w) { return __uint_as_float(w << 16); }
; __device__ __forceinline__ float bfhi(unsigned w) { return __uint_as_float(w & 0xffff0000u); }
;     __device__ __forceinline__ void operator()(Acc& acc, const Unit& u, int wr, int wc, int fr, int fq) const {
;     ...
; #pragma unroll
;         for (int ai = 0; ai < 2; ++ai)
; #pragma unroll
;             for (int m = 0; m < 4; ++m) {
;                 const int row = u.pm * BM + ai * HALF + wr * 64 + m * 16 + fr;
;                 float ss = 0.f;
; #pragma unroll
;                 for (int bj = 0; bj < 2; ++bj) {
;                     const size_t off = (size_t)row * D + col0 + bj * HALF;
;                     f32x4 r0, r1;
;                     if (RES_BF16) { const u32x4 q = rb[ai][m][bj]; r0 = (f32x4){bflo(q.x), bfhi(q.x), bflo(q.y), bfhi(q.y)}; r1 = (f32x4){bflo(q.z), bfhi(q.z), bflo(q.w), bfhi(q.w)}; }
;                     else { r0 = *(const f32x4*)(res_f32 + off); r1 = *(const f32x4*)(res_f32 + off + 4); }
;                     const f32x4 v0 = r0 + acc[ai][bj][m][0] * alpha, v1 = r1 + acc[ai][bj][m][1] * alpha;
;                     u32x4 w; w.x = pk2(v0[0], v0[1]); w.y = pk2(v0[2], v0[3]); w.z = pk2(v1[0], v1[1]); w.w = pk2(v1[2], v1[3]);
;                     *(u32x4*)((char*)XBo + xb_piece(u.pm, u.pn, wr, wc, ai, m, bj) + xlo) = w;
;                     ss += (v0[0] * v0[0] + v0[1] * v0[1]) + (v0[2] * v0[2] + v0[3] * v0[3]) + (v1[0] * v1[0] + v1[1] * v1[1]) + (v1[2] * v1[2] + v1[3] * v1[3]);
;                 }
;                 ss += __shfl_xor(ss, 16); ss += __shfl_xor(ss, 32);
;                 if (ssqp && fq == 0) ssqp[(size_t)row * 16 + u.pn * 4 + wc] = ss;
;                 if (!RES_BF16 && (m & 1)) asm volatile("" ::: "memory");
.LBB0_2304:
	s_or_b64 exec, exec, s[58:59]
	s_waitcnt vmcnt(15)
	v_lshlrev_b32_e32 v34, 16, v134
	s_waitcnt lgkmcnt(0)
	v_and_b32_e32 v35, 0xffff0000, v134
	v_lshlrev_b32_e32 v36, 16, v135
	v_and_b32_e32 v37, 0xffff0000, v135
	v_lshlrev_b32_e32 v38, 16, v136
	v_and_b32_e32 v39, 0xffff0000, v136
	v_lshlrev_b32_e32 v40, 16, v137
	v_and_b32_e32 v41, 0xffff0000, v137
	v_pk_add_f32 v[32:33], v[32:33], v[36:37]
	v_pk_add_f32 v[34:35], v[30:31], v[34:35]
	v_pk_add_f32 v[36:37], v[28:29], v[40:41]
	v_pk_add_f32 v[38:39], v[26:27], v[38:39]
	v_add_co_u32_e32 v26, vcc, s74, v212
	v_cvt_pk_bf16_f32 v28, v34, v35
	v_cvt_pk_bf16_f32 v29, v32, v33
	v_cvt_pk_bf16_f32 v30, v38, v39
	v_cvt_pk_bf16_f32 v31, v36, v37
	v_addc_co_u32_e32 v27, vcc, 0, v213, vcc
	global_store_dwordx4 v[26:27], v[28:31], off
	s_nop 1
	v_mul_f32_e32 v28, v35, v35
	v_mul_f32_e32 v29, v33, v33
	v_fmac_f32_e32 v28, v34, v34
	v_fmac_f32_e32 v29, v32, v32
	v_add_f32_e32 v28, v28, v29
	v_mul_f32_e32 v29, v39, v39
	v_fmac_f32_e32 v29, v38, v38
	v_add_f32_e32 v28, v29, v28
	v_mul_f32_e32 v29, v37, v37
	v_fmac_f32_e32 v29, v36, v36
	v_add_f32_e32 v36, v29, v28
	s_waitcnt vmcnt(15)
	v_lshlrev_b32_e32 v28, 16, v122
	v_and_b32_e32 v29, 0xffff0000, v122
	v_lshlrev_b32_e32 v30, 16, v123
	v_and_b32_e32 v31, 0xffff0000, v123
	v_pk_add_f32 v[24:25], v[24:25], v[30:31]
	v_pk_add_f32 v[22:23], v[22:23], v[28:29]
	v_lshlrev_b32_e32 v32, 16, v124
	v_and_b32_e32 v33, 0xffff0000, v124
	v_mul_f32_e32 v28, v23, v23
	v_mul_f32_e32 v29, v25, v25
	v_pk_add_f32 v[18:19], v[18:19], v[32:33]
	v_fmac_f32_e32 v28, v22, v22
	v_fmac_f32_e32 v29, v24, v24
	v_lshlrev_b32_e32 v34, 16, v125
	v_and_b32_e32 v35, 0xffff0000, v125
	v_add_f32_e32 v28, v28, v29
	v_mul_f32_e32 v29, v19, v19
	v_pk_add_f32 v[20:21], v[20:21], v[34:35]
	v_fmac_f32_e32 v29, v18, v18
	v_add_f32_e32 v28, v29, v28
	v_mul_f32_e32 v29, v21, v21
	v_fmac_f32_e32 v29, v20, v20
	v_add_f32_e32 v28, v29, v28
	v_add_f32_e32 v28, v36, v28
	ds_bpermute_b32 v29, v237, v28
	v_cvt_pk_bf16_f32 v22, v22, v23
	v_cvt_pk_bf16_f32 v23, v24, v25
	v_cvt_pk_bf16_f32 v25, v20, v21
	v_cvt_pk_bf16_f32 v24, v18, v19
	s_waitcnt lgkmcnt(0)
	v_add_f32_e32 v20, v28, v29
	ds_bpermute_b32 v21, v236, v20
	v_add_co_u32_e32 v18, vcc, s74, v126
	s_nop 1
	v_addc_co_u32_e32 v19, vcc, 0, v127, vcc
	global_store_dwordx4 v[18:19], v[22:25], off
	s_and_saveexec_b64 s[58:59], s[4:5]
	s_cbranch_execz .LBB0_2306
	v_lshl_add_u32 v22, s8, 8, v230
	v_ashrrev_i32_e32 v23, 31, v22
	s_waitcnt lgkmcnt(0)
	v_add_f32_e32 v24, v20, v21
	v_lshlrev_b64 v[20:21], 6, v[22:23]
	s_ashr_i32 s57, s56, 31
	v_lshl_add_u64 v[20:21], s[30:31], 0, v[20:21]
	v_lshl_add_u64 v[20:21], s[56:57], 2, v[20:21]
	s_lshl_b32 s26, s70, 2
	v_lshl_add_u64 v[20:21], v[20:21], 0, s[26:27]
	global_store_dword v[20:21], v24, off
.LBB0_2306:
	s_or_b64 exec, exec, s[58:59]
	s_waitcnt vmcnt(15)
	v_lshlrev_b32_e32 v20, 16, v110
	s_waitcnt lgkmcnt(0)
	v_and_b32_e32 v21, 0xffff0000, v110
	v_lshlrev_b32_e32 v22, 16, v111
	v_and_b32_e32 v23, 0xffff0000, v111
	v_lshlrev_b32_e32 v24, 16, v112
	v_and_b32_e32 v25, 0xffff0000, v112
	v_lshlrev_b32_e32 v28, 16, v113
	v_and_b32_e32 v29, 0xffff0000, v113
	v_pk_add_f32 v[14:15], v[14:15], v[20:21]
	v_pk_add_f32 v[16:17], v[16:17], v[22:23]
	v_pk_add_f32 v[20:21], v[12:13], v[28:29]
	v_pk_add_f32 v[12:13], v[10:11], v[24:25]
	v_cvt_pk_bf16_f32 v10, v14, v15
	v_mul_f32_e32 v15, v15, v15
	v_fmac_f32_e32 v15, v14, v14
	v_mul_f32_e32 v14, v17, v17
	v_fmac_f32_e32 v14, v16, v16
	v_add_f32_e32 v14, v15, v14
	v_mul_f32_e32 v15, v13, v13
	v_fmac_f32_e32 v15, v12, v12
	v_add_f32_e32 v14, v15, v14
	v_mul_f32_e32 v15, v21, v21
	v_fmac_f32_e32 v15, v20, v20
	v_cvt_pk_bf16_f32 v11, v16, v17
	v_add_f32_e32 v28, v15, v14
	s_waitcnt vmcnt(14)
	v_lshlrev_b32_e32 v14, 16, v102
	v_and_b32_e32 v15, 0xffff0000, v102
	v_lshlrev_b32_e32 v16, 16, v103
	v_and_b32_e32 v17, 0xffff0000, v103
	v_lshlrev_b32_e32 v22, 16, v104
	v_and_b32_e32 v23, 0xffff0000, v104
	v_pk_add_f32 v[8:9], v[8:9], v[16:17]
	v_pk_add_f32 v[6:7], v[6:7], v[14:15]
	v_pk_add_f32 v[16:17], v[2:3], v[22:23]
	v_mul_f32_e32 v2, v7, v7
	v_mul_f32_e32 v3, v9, v9
	v_fmac_f32_e32 v2, v6, v6
	v_fmac_f32_e32 v3, v8, v8
	v_lshlrev_b32_e32 v24, 16, v105
	v_and_b32_e32 v25, 0xffff0000, v105
	v_add_f32_e32 v2, v2, v3
	v_mul_f32_e32 v3, v17, v17
	v_pk_add_f32 v[14:15], v[4:5], v[24:25]
	v_fmac_f32_e32 v3, v16, v16
	v_add_f32_e32 v2, v3, v2
	v_mul_f32_e32 v3, v15, v15
	v_fmac_f32_e32 v3, v14, v14
	v_add_f32_e32 v2, v3, v2
	v_add_f32_e32 v2, v28, v2
	ds_bpermute_b32 v3, v237, v2
	v_cvt_pk_bf16_f32 v12, v12, v13
	v_cvt_pk_bf16_f32 v13, v20, v21
	v_cvt_pk_bf16_f32 v4, v6, v7
	v_cvt_pk_bf16_f32 v5, v8, v9
	s_waitcnt lgkmcnt(0)
	v_add_f32_e32 v2, v2, v3
	ds_bpermute_b32 v3, v236, v2
	v_cvt_pk_bf16_f32 v6, v16, v17
	v_cvt_pk_bf16_f32 v7, v14, v15
	global_store_dwordx4 v[26:27], v[10:13], off offset:2048
	global_store_dwordx4 v[18:19], v[4:7], off offset:2048
	s_and_saveexec_b64 s[58:59], s[4:5]
	s_cbranch_execz .LBB0_2308
	v_lshl_add_u32 v4, s8, 8, v231
	v_ashrrev_i32_e32 v5, 31, v4
	s_waitcnt lgkmcnt(0)
	v_add_f32_e32 v6, v2, v3
	v_lshlrev_b64 v[2:3], 6, v[4:5]
	s_ashr_i32 s57, s56, 31
	v_lshl_add_u64 v[2:3], s[30:31], 0, v[2:3]
	v_lshl_add_u64 v[2:3], s[56:57], 2, v[2:3]
	s_lshl_b32 s26, s70, 2
	v_lshl_add_u64 v[2:3], v[2:3], 0, s[26:27]
	global_store_dword v[2:3], v6, off

; __device__ __forceinline__ float bflo(unsigned w) { return __uint_as_float(w << 16); }
; __device__ __forceinline__ float bfhi(unsigned w) { return __uint_as_float(w & 0xffff0000u); }
; #define P(k) if (args.ph_hi > (k)) run_phase<k>(args, ldsp);
;     __device__ __forceinline__ void fused(Acc& acc, const Unit& u, int wr, int wc, int fr, int fq, PG8_LAS unsigned char* lds, int wid, int lane) const {
;     ...
;         u32x4 rq[2][4][2];
; #pragma unroll
;         for (int ai = 0; ai < 2; ++ai)
; #pragma unroll
;             for (int m = 0; m < 4; ++m)
; #pragma unroll
;                 for (int bj = 0; bj < 2; ++bj) rq[ai][m][bj] = *(const u32x4*)((const char*)XBr + xb_piece(u.pm, u.pn, wr, wc, ai, m, bj) + xlo);
; #pragma unroll
;         for (int ai = 0; ai < 2; ++ai)
; #pragma unroll
;             for (int m = 0; m < 4; ++m) {
;                 const int lr = ai * HALF + wr * 64 + m * 16 + fr;
;                 float ss = 0.f;
; #pragma unroll
;                 for (int bj = 0; bj < 2; ++bj) {
;                     const u32x4 rb = rq[ai][m][bj];
;                     const f32x4 r0 = {bflo(rb.x), bfhi(rb.x), bflo(rb.y), bfhi(rb.y)}, r1 = {bflo(rb.z), bfhi(rb.z), bflo(rb.w), bfhi(rb.w)};
;                     const f32x4 v0 = r0 + acc[ai][bj][m][0] * alpha, v1 = r1 + acc[ai][bj][m][1] * alpha;
;                     acc[ai][bj][m][0] = v0; acc[ai][bj][m][1] = v1;
;                     ss += (v0[0] * v0[0] + v0[1] * v0[1]) + (v0[2] * v0[2] + v0[3] * v0[3]) + (v1[0] * v1[0] + v1[1] * v1[1]) + (v1[2] * v1[2] + v1[3] * v1[3]);
;                 }
;                 ss += __shfl_xor(ss, 16); ss += __shfl_xor(ss, 32);
;                 if (fq == 0) P[lr * 4 + wc] = ss;
;             }
.LBB0_2634:
	s_lshl_b32 s52, s78, 4
	s_lshl_b32 s51, s50, 2
	s_add_i32 s51, s52, s51
	s_or_b32 s54, s51, s71
	s_ashr_i32 s55, s54, 31
	s_lshl_b64 s[56:57], s[54:55], 15
	s_or_b32 s54, s54, 2
	s_ashr_i32 s55, s54, 31
	v_lshl_add_u64 v[130:131], v[192:193], 0, s[56:57]
	s_lshl_b64 s[54:55], s[54:55], 15
	global_load_dwordx4 v[242:245], v[130:131], off
	global_load_dwordx4 v[182:185], v[130:131], off offset:2048
	v_lshl_add_u64 v[132:133], v[192:193], 0, s[54:55]
	global_load_dwordx4 v[246:249], v[132:133], off
	v_lshl_add_u64 v[134:135], v[194:195], 0, s[56:57]
	v_lshl_add_u64 v[136:137], v[196:197], 0, s[56:57]
	v_lshl_add_u64 v[138:139], v[198:199], 0, s[56:57]
	v_lshl_add_u64 v[140:141], v[200:201], 0, s[56:57]
	v_lshl_add_u64 v[142:143], v[202:203], 0, s[56:57]
	v_lshl_add_u64 v[130:131], v[194:195], 0, s[54:55]
	v_lshl_add_u64 v[144:145], v[196:197], 0, s[54:55]
	v_lshl_add_u64 v[146:147], v[198:199], 0, s[54:55]
	v_lshl_add_u64 v[148:149], v[200:201], 0, s[54:55]
	v_lshl_add_u64 v[208:209], v[204:205], 0, s[56:57]
	v_lshl_add_u64 v[240:241], v[202:203], 0, s[54:55]
	v_lshl_add_u64 v[250:251], v[204:205], 0, s[54:55]
	global_load_dwordx4 v[178:181], v[132:133], off offset:2048
	global_load_dwordx4 v[174:177], v[134:135], off
	global_load_dwordx4 v[170:173], v[130:131], off
	global_load_dwordx4 v[166:169], v[136:137], off
	global_load_dwordx4 v[162:165], v[144:145], off
	global_load_dwordx4 v[158:161], v[138:139], off
	global_load_dwordx4 v[154:157], v[146:147], off
	global_load_dwordx4 v[150:153], v[140:141], off
	s_nop 0
	global_load_dwordx4 v[146:149], v[148:149], off
	s_nop 0
	global_load_dwordx4 v[142:145], v[142:143], off
	s_nop 0
	global_load_dwordx4 v[138:141], v[240:241], off
	global_load_dwordx4 v[134:137], v[208:209], off
	global_load_dwordx4 v[130:133], v[250:251], off
	v_and_b32_e32 v209, 64, v237
	v_xor_b32_e32 v208, 16, v237
	v_add_u32_e32 v241, 64, v209
	v_cmp_lt_i32_e32 vcc, v208, v241
	s_waitcnt vmcnt(15)
	v_and_b32_e32 v209, 0xffff0000, v242
	v_cndmask_b32_e32 v208, v237, v208, vcc
	v_lshlrev_b32_e32 v240, 2, v208
	v_lshlrev_b32_e32 v208, 16, v242
	v_lshlrev_b32_e32 v242, 16, v243
	v_and_b32_e32 v243, 0xffff0000, v243
	v_lshlrev_b32_e32 v250, 16, v244
	v_and_b32_e32 v251, 0xffff0000, v244
	v_lshlrev_b32_e32 v244, 16, v245
	v_and_b32_e32 v245, 0xffff0000, v245
	v_pk_fma_f32 v[128:129], v[128:129], 0.5, v[242:243] op_sel_hi:[1,0,1]
	v_pk_fma_f32 v[126:127], v[126:127], 0.5, v[208:209] op_sel_hi:[1,0,1]
	s_waitcnt vmcnt(13)
	v_lshlrev_b32_e32 v208, 16, v246
	v_and_b32_e32 v209, 0xffff0000, v246
	v_lshlrev_b32_e32 v242, 16, v247
	v_and_b32_e32 v243, 0xffff0000, v247
	v_pk_fma_f32 v[124:125], v[124:125], 0.5, v[244:245] op_sel_hi:[1,0,1]
	v_lshlrev_b32_e32 v244, 16, v248
	v_and_b32_e32 v245, 0xffff0000, v248
	v_pk_fma_f32 v[120:121], v[120:121], 0.5, v[242:243] op_sel_hi:[1,0,1]
	v_pk_fma_f32 v[118:119], v[118:119], 0.5, v[208:209] op_sel_hi:[1,0,1]
	v_pk_fma_f32 v[122:123], v[122:123], 0.5, v[250:251] op_sel_hi:[1,0,1]
	v_lshlrev_b32_e32 v246, 16, v249
	v_and_b32_e32 v247, 0xffff0000, v249
	v_mul_f32_e32 v248, v127, v127
	v_mul_f32_e32 v249, v129, v129
	v_pk_fma_f32 v[114:115], v[114:115], 0.5, v[244:245] op_sel_hi:[1,0,1]
	v_mul_f32_e32 v208, v119, v119
	v_mul_f32_e32 v209, v121, v121
	v_mul_f32_e32 v250, v123, v123
	v_pk_fma_f32 v[116:117], v[116:117], 0.5, v[246:247] op_sel_hi:[1,0,1]
	v_fmac_f32_e32 v248, v126, v126
	v_fmac_f32_e32 v249, v128, v128
	v_mul_f32_e32 v242, v115, v115
	v_fmac_f32_e32 v208, v118, v118
	v_fmac_f32_e32 v209, v120, v120
	v_mul_f32_e32 v251, v125, v125
	v_fmac_f32_e32 v250, v122, v122
	v_mul_f32_e32 v243, v117, v117
	v_add_f32_e32 v244, v248, v249
	v_fmac_f32_e32 v242, v114, v114
	v_add_f32_e32 v208, v208, v209
	v_fmac_f32_e32 v251, v124, v124
	v_add_f32_e32 v244, v250, v244
	v_add_f32_e32 v208, v242, v208
	v_fmac_f32_e32 v243, v116, v116
	v_add_f32_e32 v209, v251, v244
	v_add_f32_e32 v208, v243, v208
	v_add_f32_e32 v208, v209, v208
	ds_bpermute_b32 v209, v240, v208
	v_xor_b32_e32 v242, 32, v237
	v_cmp_lt_i32_e32 vcc, v242, v241
	s_nop 1
	v_cndmask_b32_e32 v241, v237, v242, vcc
	v_lshlrev_b32_e32 v241, 2, v241
	s_waitcnt lgkmcnt(0)
	v_add_f32_e32 v242, v208, v209
	ds_bpermute_b32 v243, v241, v242
	s_and_saveexec_b64 s[54:55], s[4:5]
	s_cbranch_execz .LBB0_2636
	s_waitcnt lgkmcnt(0)
	v_add_f32_e32 v208, v242, v243
	ds_write_b32 v239, v208
.LBB0_2636:
	s_or_b64 exec, exec, s[54:55]
	v_lshlrev_b32_e32 v208, 16, v182
	v_and_b32_e32 v209, 0xffff0000, v182
	v_lshlrev_b32_e32 v182, 16, v183
	v_and_b32_e32 v183, 0xffff0000, v183
	v_pk_fma_f32 v[112:113], v[112:113], 0.5, v[182:183] op_sel_hi:[1,0,1]
	v_pk_fma_f32 v[110:111], v[110:111], 0.5, v[208:209] op_sel_hi:[1,0,1]
	v_lshlrev_b32_e32 v242, 16, v184
	s_waitcnt lgkmcnt(0)
	v_and_b32_e32 v243, 0xffff0000, v184
	v_mul_f32_e32 v182, v111, v111
	v_mul_f32_e32 v183, v113, v113
	v_pk_fma_f32 v[106:107], v[106:107], 0.5, v[242:243] op_sel_hi:[1,0,1]
	v_fmac_f32_e32 v182, v110, v110
	v_fmac_f32_e32 v183, v112, v112
	v_lshlrev_b32_e32 v184, 16, v185
	v_and_b32_e32 v185, 0xffff0000, v185
	v_add_f32_e32 v182, v182, v183
	v_mul_f32_e32 v183, v107, v107
	v_pk_fma_f32 v[108:109], v[108:109], 0.5, v[184:185] op_sel_hi:[1,0,1]
	v_fmac_f32_e32 v183, v106, v106
	v_add_f32_e32 v182, v183, v182
	v_mul_f32_e32 v183, v109, v109
	v_fmac_f32_e32 v183, v108, v108
	v_add_f32_e32 v208, v183, v182
	s_waitcnt vmcnt(12)
	v_lshlrev_b32_e32 v182, 16, v178
	v_and_b32_e32 v183, 0xffff0000, v178
	v_lshlrev_b32_e32 v178, 16, v179
	v_and_b32_e32 v179, 0xffff0000, v179
	v_pk_fma_f32 v[104:105], v[104:105], 0.5, v[178:179] op_sel_hi:[1,0,1]
	v_pk_fma_f32 v[102:103], v[102:103], 0.5, v[182:183] op_sel_hi:[1,0,1]
	v_lshlrev_b32_e32 v184, 16, v180
	v_and_b32_e32 v185, 0xffff0000, v180
	v_mul_f32_e32 v178, v103, v103
	v_mul_f32_e32 v179, v105, v105
	v_pk_fma_f32 v[98:99], v[98:99], 0.5, v[184:185] op_sel_hi:[1,0,1]
	v_fmac_f32_e32 v178, v102, v102
	v_fmac_f32_e32 v179, v104, v104
	v_lshlrev_b32_e32 v180, 16, v181
	v_and_b32_e32 v181, 0xffff0000, v181
	v_add_f32_e32 v178, v178, v179
	v_mul_f32_e32 v179, v99, v99
	v_pk_fma_f32 v[100:101], v[100:101], 0.5, v[180:181] op_sel_hi:[1,0,1]
	v_fmac_f32_e32 v179, v98, v98
	v_add_f32_e32 v178, v179, v178
	v_mul_f32_e32 v179, v101, v101
	v_fmac_f32_e32 v179, v100, v100
	v_add_f32_e32 v178, v179, v178
	v_add_f32_e32 v178, v208, v178
	ds_bpermute_b32 v179, v240, v178
	s_waitcnt lgkmcnt(0)
	v_add_f32_e32 v178, v178, v179
	ds_bpermute_b32 v179, v241, v178
	s_and_saveexec_b64 s[54:55], s[4:5]
	s_cbranch_execz .LBB0_2638
	s_waitcnt lgkmcnt(0)
	v_add_f32_e32 v178, v178, v179
	ds_write_b32 v239, v178 offset:256
; __device__ __forceinline__ float bflo(unsigned w) { return __uint_as_float(w << 16); }
; __device__ __forceinline__ float bfhi(unsigned w) { return __uint_as_float(w & 0xffff0000u); }
; #define P(k) if (args.ph_hi > (k)) run_phase<k>(args, ldsp);
;     __device__ __forceinline__ void fused(Acc& acc, const Unit& u, int wr, int wc, int fr, int fq, PG8_LAS unsigned char* lds, int wid, int lane) const {
;     ...
; #pragma unroll
;         for (int ai = 0; ai < 2; ++ai)
; #pragma unroll
;             for (int m = 0; m < 4; ++m) {
;                 const int lr = ai * HALF + wr * 64 + m * 16 + fr;
;                 float ss = 0.f;
; #pragma unroll
;                 for (int bj = 0; bj < 2; ++bj) {
;                     const u32x4 rb = rq[ai][m][bj];
;                     const f32x4 r0 = {bflo(rb.x), bfhi(rb.x), bflo(rb.y), bfhi(rb.y)}, r1 = {bflo(rb.z), bfhi(rb.z), bflo(rb.w), bfhi(rb.w)};
;                     const f32x4 v0 = r0 + acc[ai][bj][m][0] * alpha, v1 = r1 + acc[ai][bj][m][1] * alpha;
;                     acc[ai][bj][m][0] = v0; acc[ai][bj][m][1] = v1;
;                     ss += (v0[0] * v0[0] + v0[1] * v0[1]) + (v0[2] * v0[2] + v0[3] * v0[3]) + (v1[0] * v1[0] + v1[1] * v1[1]) + (v1[2] * v1[2] + v1[3] * v1[3]);
;                 }
;                 ss += __shfl_xor(ss, 16); ss += __shfl_xor(ss, 32);
;                 if (fq == 0) P[lr * 4 + wc] = ss;
;             }
.LBB0_2638:
	s_or_b64 exec, exec, s[54:55]
	s_waitcnt vmcnt(11)
	v_lshlrev_b32_e32 v178, 16, v174
	s_waitcnt lgkmcnt(0)
	v_and_b32_e32 v179, 0xffff0000, v174
	v_lshlrev_b32_e32 v174, 16, v175
	v_and_b32_e32 v175, 0xffff0000, v175
	v_pk_fma_f32 v[96:97], v[96:97], 0.5, v[174:175] op_sel_hi:[1,0,1]
	v_pk_fma_f32 v[94:95], v[94:95], 0.5, v[178:179] op_sel_hi:[1,0,1]
	v_lshlrev_b32_e32 v180, 16, v176
	v_and_b32_e32 v181, 0xffff0000, v176
	v_mul_f32_e32 v174, v95, v95
	v_mul_f32_e32 v175, v97, v97
	v_pk_fma_f32 v[90:91], v[90:91], 0.5, v[180:181] op_sel_hi:[1,0,1]
	v_fmac_f32_e32 v174, v94, v94
	v_fmac_f32_e32 v175, v96, v96
	v_lshlrev_b32_e32 v176, 16, v177
	v_and_b32_e32 v177, 0xffff0000, v177
	v_add_f32_e32 v174, v174, v175
	v_mul_f32_e32 v175, v91, v91
	v_pk_fma_f32 v[92:93], v[92:93], 0.5, v[176:177] op_sel_hi:[1,0,1]
	v_fmac_f32_e32 v175, v90, v90
	v_add_f32_e32 v174, v175, v174
	v_mul_f32_e32 v175, v93, v93
	v_fmac_f32_e32 v175, v92, v92
	v_add_f32_e32 v178, v175, v174
	s_waitcnt vmcnt(10)
	v_lshlrev_b32_e32 v174, 16, v170
	v_and_b32_e32 v175, 0xffff0000, v170
	v_lshlrev_b32_e32 v170, 16, v171
	v_and_b32_e32 v171, 0xffff0000, v171
	v_pk_fma_f32 v[88:89], v[88:89], 0.5, v[170:171] op_sel_hi:[1,0,1]
	v_pk_fma_f32 v[86:87], v[86:87], 0.5, v[174:175] op_sel_hi:[1,0,1]
	v_lshlrev_b32_e32 v176, 16, v172
	v_and_b32_e32 v177, 0xffff0000, v172
	v_mul_f32_e32 v170, v87, v87
	v_mul_f32_e32 v171, v89, v89
	v_pk_fma_f32 v[82:83], v[82:83], 0.5, v[176:177] op_sel_hi:[1,0,1]
	v_fmac_f32_e32 v170, v86, v86
	v_fmac_f32_e32 v171, v88, v88
	v_lshlrev_b32_e32 v172, 16, v173
	v_and_b32_e32 v173, 0xffff0000, v173
	v_add_f32_e32 v170, v170, v171
	v_mul_f32_e32 v171, v83, v83
	v_pk_fma_f32 v[84:85], v[84:85], 0.5, v[172:173] op_sel_hi:[1,0,1]
	v_fmac_f32_e32 v171, v82, v82
	v_add_f32_e32 v170, v171, v170
	v_mul_f32_e32 v171, v85, v85
	v_fmac_f32_e32 v171, v84, v84
	v_add_f32_e32 v170, v171, v170
	v_add_f32_e32 v170, v178, v170
	ds_bpermute_b32 v171, v240, v170
	s_waitcnt lgkmcnt(0)
	v_add_f32_e32 v170, v170, v171
	ds_bpermute_b32 v171, v241, v170
	s_and_saveexec_b64 s[54:55], s[4:5]
	s_cbranch_execz .LBB0_2640
	s_waitcnt lgkmcnt(0)
	v_add_f32_e32 v170, v170, v171
	ds_write_b32 v239, v170 offset:512
.LBB0_2640:
	s_or_b64 exec, exec, s[54:55]
	s_waitcnt vmcnt(9)
	v_lshlrev_b32_e32 v170, 16, v166
	s_waitcnt lgkmcnt(0)
	v_and_b32_e32 v171, 0xffff0000, v166
	v_lshlrev_b32_e32 v166, 16, v167
	v_and_b32_e32 v167, 0xffff0000, v167
	v_pk_fma_f32 v[80:81], v[80:81], 0.5, v[166:167] op_sel_hi:[1,0,1]
	v_pk_fma_f32 v[78:79], v[78:79], 0.5, v[170:171] op_sel_hi:[1,0,1]
	v_lshlrev_b32_e32 v172, 16, v168
	v_and_b32_e32 v173, 0xffff0000, v168
	v_mul_f32_e32 v166, v79, v79
	v_mul_f32_e32 v167, v81, v81
	v_pk_fma_f32 v[74:75], v[74:75], 0.5, v[172:173] op_sel_hi:[1,0,1]
	v_fmac_f32_e32 v166, v78, v78
	v_fmac_f32_e32 v167, v80, v80
	v_lshlrev_b32_e32 v168, 16, v169
	v_and_b32_e32 v169, 0xffff0000, v169
	v_add_f32_e32 v166, v166, v167
	v_mul_f32_e32 v167, v75, v75
	v_pk_fma_f32 v[76:77], v[76:77], 0.5, v[168:169] op_sel_hi:[1,0,1]
	v_fmac_f32_e32 v167, v74, v74
	v_add_f32_e32 v166, v167, v166
	v_mul_f32_e32 v167, v77, v77
	v_fmac_f32_e32 v167, v76, v76
	v_add_f32_e32 v170, v167, v166
	s_waitcnt vmcnt(8)
	v_lshlrev_b32_e32 v166, 16, v162
	v_and_b32_e32 v167, 0xffff0000, v162
	v_lshlrev_b32_e32 v162, 16, v163
	v_and_b32_e32 v163, 0xffff0000, v163
	v_pk_fma_f32 v[72:73], v[72:73], 0.5, v[162:163] op_sel_hi:[1,0,1]
	v_pk_fma_f32 v[70:71], v[70:71], 0.5, v[166:167] op_sel_hi:[1,0,1]
	v_lshlrev_b32_e32 v168, 16, v164
	v_and_b32_e32 v169, 0xffff0000, v164
	v_mul_f32_e32 v162, v71, v71
	v_mul_f32_e32 v163, v73, v73
	v_pk_fma_f32 v[66:67], v[66:67], 0.5, v[168:169] op_sel_hi:[1,0,1]
	v_fmac_f32_e32 v162, v70, v70
	v_fmac_f32_e32 v163, v72, v72
	v_lshlrev_b32_e32 v164, 16, v165
	v_and_b32_e32 v165, 0xffff0000, v165
	v_add_f32_e32 v162, v162, v163
	v_mul_f32_e32 v163, v67, v67
	v_pk_fma_f32 v[68:69], v[68:69], 0.5, v[164:165] op_sel_hi:[1,0,1]
	v_fmac_f32_e32 v163, v66, v66
	v_add_f32_e32 v162, v163, v162
	v_mul_f32_e32 v163, v69, v69
	v_fmac_f32_e32 v163, v68, v68
	v_add_f32_e32 v162, v163, v162
	v_add_f32_e32 v162, v170, v162
	ds_bpermute_b32 v163, v240, v162
	s_waitcnt lgkmcnt(0)
	v_add_f32_e32 v162, v162, v163
	ds_bpermute_b32 v163, v241, v162
	s_and_saveexec_b64 s[54:55], s[4:5]
	s_cbranch_execz .LBB0_2642
	s_waitcnt lgkmcnt(0)
	v_add_f32_e32 v162, v162, v163
	ds_write_b32 v239, v162 offset:768
.LBB0_2642:
	s_or_b64 exec, exec, s[54:55]
	s_waitcnt vmcnt(7)
	v_lshlrev_b32_e32 v162, 16, v158
	s_waitcnt lgkmcnt(0)
	v_and_b32_e32 v163, 0xffff0000, v158
	v_lshlrev_b32_e32 v158, 16, v159
	v_and_b32_e32 v159, 0xffff0000, v159
	v_pk_fma_f32 v[64:65], v[64:65], 0.5, v[158:159] op_sel_hi:[1,0,1]
	v_pk_fma_f32 v[62:63], v[62:63], 0.5, v[162:163] op_sel_hi:[1,0,1]
	v_lshlrev_b32_e32 v164, 16, v160
	v_and_b32_e32 v165, 0xffff0000, v160
	v_mul_f32_e32 v158, v63, v63
	v_mul_f32_e32 v159, v65, v65
	v_pk_fma_f32 v[58:59], v[58:59], 0.5, v[164:165] op_sel_hi:[1,0,1]
	v_fmac_f32_e32 v158, v62, v62
	v_fmac_f32_e32 v159, v64, v64
	v_lshlrev_b32_e32 v160, 16, v161
	v_and_b32_e32 v161, 0xffff0000, v161
	v_add_f32_e32 v158, v158, v159
	v_mul_f32_e32 v159, v59, v59
	v_pk_fma_f32 v[60:61], v[60:61], 0.5, v[160:161] op_sel_hi:[1,0,1]
	v_fmac_f32_e32 v159, v58, v58
	v_add_f32_e32 v158, v159, v158
	v_mul_f32_e32 v159, v61, v61
	v_fmac_f32_e32 v159, v60, v60
	v_add_f32_e32 v162, v159, v158
	s_waitcnt vmcnt(6)
	v_lshlrev_b32_e32 v158, 16, v154
	v_and_b32_e32 v159, 0xffff0000, v154
	v_lshlrev_b32_e32 v154, 16, v155
	v_and_b32_e32 v155, 0xffff0000, v155
	v_pk_fma_f32 v[56:57], v[56:57], 0.5, v[154:155] op_sel_hi:[1,0,1]
	v_pk_fma_f32 v[54:55], v[54:55], 0.5, v[158:159] op_sel_hi:[1,0,1]
	v_lshlrev_b32_e32 v160, 16, v156
	v_and_b32_e32 v161, 0xffff0000, v156
	v_mul_f32_e32 v154, v55, v55
	v_mul_f32_e32 v155, v57, v57
	v_pk_fma_f32 v[50:51], v[50:51], 0.5, v[160:161] op_sel_hi:[1,0,1]
	v_fmac_f32_e32 v154, v54, v54
	v_fmac_f32_e32 v155, v56, v56
	v_lshlrev_b32_e32 v156, 16, v157
	v_and_b32_e32 v157, 0xffff0000, v157
	v_add_f32_e32 v154, v154, v155
	v_mul_f32_e32 v155, v51, v51
	v_pk_fma_f32 v[52:53], v[52:53], 0.5, v[156:157] op_sel_hi:[1,0,1]
	v_fmac_f32_e32 v155, v50, v50
	v_add_f32_e32 v154, v155, v154
	v_mul_f32_e32 v155, v53, v53
	v_fmac_f32_e32 v155, v52, v52
	v_add_f32_e32 v154, v155, v154
	v_add_f32_e32 v154, v162, v154
	ds_bpermute_b32 v155, v240, v154
	s_waitcnt lgkmcnt(0)
	v_add_f32_e32 v154, v154, v155
	ds_bpermute_b32 v155, v241, v154
	s_and_saveexec_b64 s[54:55], s[4:5]
	s_cbranch_execz .LBB0_2644
	s_waitcnt lgkmcnt(0)
	v_add_f32_e32 v154, v154, v155
	ds_write_b32 v239, v154 offset:2048
; __device__ __forceinline__ float bflo(unsigned w) { return __uint_as_float(w << 16); }
; __device__ __forceinline__ float bfhi(unsigned w) { return __uint_as_float(w & 0xffff0000u); }
; #define P(k) if (args.ph_hi > (k)) run_phase<k>(args, ldsp);
;     __device__ __forceinline__ void fused(Acc& acc, const Unit& u, int wr, int wc, int fr, int fq, PG8_LAS unsigned char* lds, int wid, int lane) const {
;     ...
; #pragma unroll
;         for (int ai = 0; ai < 2; ++ai)
; #pragma unroll
;             for (int m = 0; m < 4; ++m) {
;                 const int lr = ai * HALF + wr * 64 + m * 16 + fr;
;                 float ss = 0.f;
; #pragma unroll
;                 for (int bj = 0; bj < 2; ++bj) {
;                     const u32x4 rb = rq[ai][m][bj];
;                     const f32x4 r0 = {bflo(rb.x), bfhi(rb.x), bflo(rb.y), bfhi(rb.y)}, r1 = {bflo(rb.z), bfhi(rb.z), bflo(rb.w), bfhi(rb.w)};
;                     const f32x4 v0 = r0 + acc[ai][bj][m][0] * alpha, v1 = r1 + acc[ai][bj][m][1] * alpha;
;                     acc[ai][bj][m][0] = v0; acc[ai][bj][m][1] = v1;
;                     ss += (v0[0] * v0[0] + v0[1] * v0[1]) + (v0[2] * v0[2] + v0[3] * v0[3]) + (v1[0] * v1[0] + v1[1] * v1[1]) + (v1[2] * v1[2] + v1[3] * v1[3]);
;                 }
;                 ss += __shfl_xor(ss, 16); ss += __shfl_xor(ss, 32);
;                 if (fq == 0) P[lr * 4 + wc] = ss;
;             }
.LBB0_2644:
	s_or_b64 exec, exec, s[54:55]
	s_waitcnt vmcnt(5)
	v_lshlrev_b32_e32 v154, 16, v150
	s_waitcnt lgkmcnt(0)
	v_and_b32_e32 v155, 0xffff0000, v150
	v_lshlrev_b32_e32 v150, 16, v151
	v_and_b32_e32 v151, 0xffff0000, v151
	v_pk_fma_f32 v[48:49], v[48:49], 0.5, v[150:151] op_sel_hi:[1,0,1]
	v_pk_fma_f32 v[46:47], v[46:47], 0.5, v[154:155] op_sel_hi:[1,0,1]
	v_lshlrev_b32_e32 v156, 16, v152
	v_and_b32_e32 v157, 0xffff0000, v152
	v_mul_f32_e32 v150, v47, v47
	v_mul_f32_e32 v151, v49, v49
	v_pk_fma_f32 v[42:43], v[42:43], 0.5, v[156:157] op_sel_hi:[1,0,1]
	v_fmac_f32_e32 v150, v46, v46
	v_fmac_f32_e32 v151, v48, v48
	v_lshlrev_b32_e32 v152, 16, v153
	v_and_b32_e32 v153, 0xffff0000, v153
	v_add_f32_e32 v150, v150, v151
	v_mul_f32_e32 v151, v43, v43
	v_pk_fma_f32 v[44:45], v[44:45], 0.5, v[152:153] op_sel_hi:[1,0,1]
	v_fmac_f32_e32 v151, v42, v42
	v_add_f32_e32 v150, v151, v150
	v_mul_f32_e32 v151, v45, v45
	v_fmac_f32_e32 v151, v44, v44
	v_add_f32_e32 v154, v151, v150
	s_waitcnt vmcnt(4)
	v_lshlrev_b32_e32 v150, 16, v146
	v_and_b32_e32 v151, 0xffff0000, v146
	v_lshlrev_b32_e32 v146, 16, v147
	v_and_b32_e32 v147, 0xffff0000, v147
	v_pk_fma_f32 v[40:41], v[40:41], 0.5, v[146:147] op_sel_hi:[1,0,1]
	v_pk_fma_f32 v[38:39], v[38:39], 0.5, v[150:151] op_sel_hi:[1,0,1]
	v_lshlrev_b32_e32 v152, 16, v148
	v_and_b32_e32 v153, 0xffff0000, v148
	v_mul_f32_e32 v146, v39, v39
	v_mul_f32_e32 v147, v41, v41
	v_pk_fma_f32 v[34:35], v[34:35], 0.5, v[152:153] op_sel_hi:[1,0,1]
	v_fmac_f32_e32 v146, v38, v38
	v_fmac_f32_e32 v147, v40, v40
	v_lshlrev_b32_e32 v148, 16, v149
	v_and_b32_e32 v149, 0xffff0000, v149
	v_add_f32_e32 v146, v146, v147
	v_mul_f32_e32 v147, v35, v35
	v_pk_fma_f32 v[36:37], v[36:37], 0.5, v[148:149] op_sel_hi:[1,0,1]
	v_fmac_f32_e32 v147, v34, v34
	v_add_f32_e32 v146, v147, v146
	v_mul_f32_e32 v147, v37, v37
	v_fmac_f32_e32 v147, v36, v36
	v_add_f32_e32 v146, v147, v146
	v_add_f32_e32 v146, v154, v146
	ds_bpermute_b32 v147, v240, v146
	s_waitcnt lgkmcnt(0)
	v_add_f32_e32 v146, v146, v147
	ds_bpermute_b32 v147, v241, v146
	s_and_saveexec_b64 s[54:55], s[4:5]
	s_cbranch_execz .LBB0_2646
	s_waitcnt lgkmcnt(0)
	v_add_f32_e32 v146, v146, v147
	ds_write_b32 v239, v146 offset:2304
.LBB0_2646:
	s_or_b64 exec, exec, s[54:55]
	s_waitcnt vmcnt(3)
	v_lshlrev_b32_e32 v146, 16, v142
	s_waitcnt lgkmcnt(0)
	v_and_b32_e32 v147, 0xffff0000, v142
	v_lshlrev_b32_e32 v142, 16, v143
	v_and_b32_e32 v143, 0xffff0000, v143
	v_pk_fma_f32 v[32:33], v[32:33], 0.5, v[142:143] op_sel_hi:[1,0,1]
	v_pk_fma_f32 v[30:31], v[30:31], 0.5, v[146:147] op_sel_hi:[1,0,1]
	v_lshlrev_b32_e32 v148, 16, v144
	v_and_b32_e32 v149, 0xffff0000, v144
	v_mul_f32_e32 v142, v31, v31
	v_mul_f32_e32 v143, v33, v33
	v_pk_fma_f32 v[26:27], v[26:27], 0.5, v[148:149] op_sel_hi:[1,0,1]
	v_fmac_f32_e32 v142, v30, v30
	v_fmac_f32_e32 v143, v32, v32
	v_lshlrev_b32_e32 v144, 16, v145
	v_and_b32_e32 v145, 0xffff0000, v145
	v_add_f32_e32 v142, v142, v143
	v_mul_f32_e32 v143, v27, v27
	v_pk_fma_f32 v[28:29], v[28:29], 0.5, v[144:145] op_sel_hi:[1,0,1]
	v_fmac_f32_e32 v143, v26, v26
	v_add_f32_e32 v142, v143, v142
	v_mul_f32_e32 v143, v29, v29
	v_fmac_f32_e32 v143, v28, v28
	v_add_f32_e32 v146, v143, v142
	s_waitcnt vmcnt(2)
	v_lshlrev_b32_e32 v142, 16, v138
	v_and_b32_e32 v143, 0xffff0000, v138
	v_lshlrev_b32_e32 v138, 16, v139
	v_and_b32_e32 v139, 0xffff0000, v139
	v_pk_fma_f32 v[24:25], v[24:25], 0.5, v[138:139] op_sel_hi:[1,0,1]
	v_pk_fma_f32 v[22:23], v[22:23], 0.5, v[142:143] op_sel_hi:[1,0,1]
	v_lshlrev_b32_e32 v144, 16, v140
	v_and_b32_e32 v145, 0xffff0000, v140
	v_mul_f32_e32 v138, v23, v23
	v_mul_f32_e32 v139, v25, v25
	v_pk_fma_f32 v[18:19], v[18:19], 0.5, v[144:145] op_sel_hi:[1,0,1]
	v_fmac_f32_e32 v138, v22, v22
	v_fmac_f32_e32 v139, v24, v24
	v_lshlrev_b32_e32 v140, 16, v141
	v_and_b32_e32 v141, 0xffff0000, v141
	v_add_f32_e32 v138, v138, v139
	v_mul_f32_e32 v139, v19, v19
	v_pk_fma_f32 v[20:21], v[20:21], 0.5, v[140:141] op_sel_hi:[1,0,1]
	v_fmac_f32_e32 v139, v18, v18
	v_add_f32_e32 v138, v139, v138
	v_mul_f32_e32 v139, v21, v21
	v_fmac_f32_e32 v139, v20, v20
	v_add_f32_e32 v138, v139, v138
	v_add_f32_e32 v138, v146, v138
	ds_bpermute_b32 v139, v240, v138
	s_waitcnt lgkmcnt(0)
	v_add_f32_e32 v138, v138, v139
	ds_bpermute_b32 v139, v241, v138
	s_and_saveexec_b64 s[54:55], s[4:5]
	s_cbranch_execz .LBB0_2648
	s_waitcnt lgkmcnt(0)
	v_add_f32_e32 v138, v138, v139
	ds_write_b32 v239, v138 offset:2560
.LBB0_2648:
	s_or_b64 exec, exec, s[54:55]
	s_waitcnt vmcnt(1)
	v_lshlrev_b32_e32 v140, 16, v134
	v_and_b32_e32 v141, 0xffff0000, v134
	v_lshlrev_b32_e32 v134, 16, v135
	v_and_b32_e32 v135, 0xffff0000, v135
	v_lshlrev_b32_e32 v142, 16, v136
	v_and_b32_e32 v143, 0xffff0000, v136
	v_lshlrev_b32_e32 v136, 16, v137
	v_and_b32_e32 v137, 0xffff0000, v137
	s_waitcnt lgkmcnt(0)
	v_pk_fma_f32 v[138:139], v[16:17], 0.5, v[134:135] op_sel_hi:[1,0,1]
	v_pk_fma_f32 v[140:141], v[14:15], 0.5, v[140:141] op_sel_hi:[1,0,1]
	v_pk_fma_f32 v[134:135], v[12:13], 0.5, v[136:137] op_sel_hi:[1,0,1]
	v_pk_fma_f32 v[136:137], v[10:11], 0.5, v[142:143] op_sel_hi:[1,0,1]
	v_mul_f32_e32 v10, v141, v141
	v_mul_f32_e32 v11, v139, v139
	v_fmac_f32_e32 v10, v140, v140
	v_fmac_f32_e32 v11, v138, v138
	v_add_f32_e32 v10, v10, v11
	v_mul_f32_e32 v11, v137, v137
	v_fmac_f32_e32 v11, v136, v136
	v_add_f32_e32 v10, v11, v10
	v_mul_f32_e32 v11, v135, v135
	v_fmac_f32_e32 v11, v134, v134
	v_add_f32_e32 v146, v11, v10
	s_waitcnt vmcnt(0)
	v_lshlrev_b32_e32 v10, 16, v130
	v_and_b32_e32 v11, 0xffff0000, v130
	v_lshlrev_b32_e32 v12, 16, v131
	v_and_b32_e32 v13, 0xffff0000, v131
	v_lshlrev_b32_e32 v14, 16, v132
	v_and_b32_e32 v15, 0xffff0000, v132
	v_pk_fma_f32 v[142:143], v[8:9], 0.5, v[12:13] op_sel_hi:[1,0,1]
	v_pk_fma_f32 v[144:145], v[6:7], 0.5, v[10:11] op_sel_hi:[1,0,1]
	v_lshlrev_b32_e32 v16, 16, v133
	v_and_b32_e32 v17, 0xffff0000, v133
	v_pk_fma_f32 v[132:133], v[2:3], 0.5, v[14:15] op_sel_hi:[1,0,1]
	v_mul_f32_e32 v2, v145, v145
	v_mul_f32_e32 v3, v143, v143
	v_fmac_f32_e32 v2, v144, v144
	v_fmac_f32_e32 v3, v142, v142
	v_add_f32_e32 v2, v2, v3
	v_mul_f32_e32 v3, v133, v133
	v_pk_fma_f32 v[130:131], v[4:5], 0.5, v[16:17] op_sel_hi:[1,0,1]
	v_fmac_f32_e32 v3, v132, v132
	v_add_f32_e32 v2, v3, v2
	v_mul_f32_e32 v3, v131, v131
	v_fmac_f32_e32 v3, v130, v130
	v_add_f32_e32 v2, v3, v2
	v_add_f32_e32 v2, v146, v2
	ds_bpermute_b32 v3, v240, v2
	s_waitcnt lgkmcnt(0)
	v_add_f32_e32 v2, v2, v3
	ds_bpermute_b32 v3, v241, v2
	s_and_saveexec_b64 s[54:55], s[4:5]
	s_cbranch_execz .LBB0_2650
	s_waitcnt lgkmcnt(0)
	v_add_f32_e32 v2, v2, v3
	ds_write_b32 v239, v2 offset:2816
